# ffn_up rewritten by hand as 256x128 block tile (128x64 wave tile), A double-buffered + B single-buffered in 80KB LDS, bf16 MFMA fp32 acc unchanged
# speedup vs baseline: 1.0338x; 1.0299x over previous
; __device__ __forceinline__ int otid() { int t = threadIdx.x; asm volatile("" : "+v"(t)); return t; }
; __device__ __forceinline__ int frag_off(int fr, int fq) { return (fr >> 3) * 1024 + (fr & 7) * 128 + ((fq ^ ((fr >> 1) & 7)) << 4); }
;   const int tid = otid(), lane = tid & 63, wid = tid >> 6, wr = wid >> 1, wc = wid & 1, fr = lane & 15, fq = lane >> 4;
;   const int o0 = tid * 16;
;   const int lrow = (o0 >> 10) * 8 + ((o0 >> 7) & 7), lcol = ((((o0 >> 4) & 7) ^ ((lrow >> 1) & 7))) * 8;
;   const bf16_t* ag = A + (size_t)lrow * lda + lcol;
;   const bf16_t* bg = Bt + (size_t)lrow * ldb + lcol;
;   const char* A8 = (const char*)A;
;   const char* B8 = (const char*)Bt;
;   unsigned aoff[4], boff[NT];
; #pragma unroll
;   for (int i = 0; i < 4; ++i) aoff[i] = (unsigned)(((lrow + 32 * i) * lda + lcol) * 2);
; #pragma unroll
;   for (int i = 0; i < NT; ++i) boff[i] = (unsigned)(((lrow + (i & 1) * bs1 + (i >> 1) * bs2) * ldb + lcol) * 2);
;   const int wbase = __builtin_amdgcn_readfirstlane(wid) * 1024;
;   const int inner = frag_off(fr, fq);
;   const int abase = wr * 8192 + inner;
;   const int bbase = 16384 + wc * (NT * 2048) + inner;
;   const int nk = K >> 6;
; __device__ __forceinline__ void phase_ffn_up(const Params& p, int half, int mrows, char* smem, unsigned* tk) {
;   TILE_IDS; (void)tid;
;   const bf16_t* H = WS_BF(p, OFF_H);
;   const bf16_t* W = WS_BF(p, OFF_W) + W_UP + (size_t)half * 5632 * 1024;
;   bf16_t* ACT = WS_BF(p, OFF_P);
;   for (TileIter ti(mrows / 128, 44, 4, 11, tk); ti.valid();) {
;     int tm, tn; ti.get(tm, tn);
;     ti.prefetch();
;     f32x4 acc[4][4];
;     zero_acc<4>(acc);
;     gemm_main<4>(H + (size_t)tm * 128 * DM, DM, W + (size_t)tn * 128 * DM, DM, DM, acc, smem);
.LBB0_316:
	v_readlane_b32 s52, v250, 29
	s_andn2_b64 vcc, exec, s[92:93]
	v_readlane_b32 s53, v250, 30
	s_mov_b64 s[44:45], 0x1000
	s_cbranch_vccnz .LBB0_329
	s_lshr_b32 s23, s22, 10
	s_cmp_eq_u32 s77, 1
	s_cselect_b64 s[36:37], -1, 0
	s_mul_i32 s23, s23, 44
	s_and_b64 s[40:41], s[36:37], exec
	s_cselect_b32 s23, 0x630, s23
	v_mov_b32_e32 v0, v172
	s_cmp_ge_u32 s39, s23
	s_cbranch_scc1 .LBB0_329
	s_lshl_b32 s98, s91, 3
	s_and_b64 s[36:37], s[36:37], exec
	s_cselect_b32 s40, 0, 0xb00000
	s_lshl_b64 s[36:37], s[98:99], 2
	v_readlane_b32 s42, v251, 3
	s_add_u32 s36, s42, s36
	v_readlane_b32 s42, v251, 4
	s_addc_u32 s37, s42, s37
	s_waitcnt vmcnt(0) lgkmcnt(0)
	s_lshr_b32 s23, s23, 1
	v_writelane_b32 v249, s40, 42
	v_readfirstlane_b32 s40, v92
	v_readfirstlane_b32 s41, v93
	v_readfirstlane_b32 s42, v94
	v_readfirstlane_b32 s43, v95
	v_readfirstlane_b32 s44, v96
	v_readfirstlane_b32 s45, v97
	v_readfirstlane_b32 s46, v98
	v_readfirstlane_b32 s47, v99
	v_writelane_b32 v249, s40, 0
	v_writelane_b32 v249, s41, 1
	v_writelane_b32 v249, s42, 2
	v_writelane_b32 v249, s43, 3
	v_writelane_b32 v249, s44, 4
	v_writelane_b32 v249, s45, 5
	v_writelane_b32 v249, s46, 6
	v_writelane_b32 v249, s47, 7
	v_readfirstlane_b32 s40, v100
	v_readfirstlane_b32 s41, v101
	v_readfirstlane_b32 s42, v102
	v_readfirstlane_b32 s43, v103
	v_readfirstlane_b32 s44, v104
	v_readfirstlane_b32 s45, v105
	v_readfirstlane_b32 s46, v106
	v_readfirstlane_b32 s47, v107
	v_writelane_b32 v249, s40, 8
	v_writelane_b32 v249, s41, 9
	v_writelane_b32 v249, s42, 10
	v_writelane_b32 v249, s43, 11
	v_writelane_b32 v249, s44, 12
	v_writelane_b32 v249, s45, 13
	v_writelane_b32 v249, s46, 14
	v_writelane_b32 v249, s47, 15
	v_readfirstlane_b32 s40, v108
	v_readfirstlane_b32 s41, v109
	v_readfirstlane_b32 s42, v110
	v_readfirstlane_b32 s43, v111
	v_readfirstlane_b32 s44, v112
	v_readfirstlane_b32 s45, v113
	v_readfirstlane_b32 s46, v114
	v_readfirstlane_b32 s47, v115
	v_writelane_b32 v249, s40, 16
	v_writelane_b32 v249, s41, 17
	v_writelane_b32 v249, s42, 18
	v_writelane_b32 v249, s43, 19
	v_writelane_b32 v249, s44, 20
	v_writelane_b32 v249, s45, 21
	v_writelane_b32 v249, s46, 22
	v_writelane_b32 v249, s47, 23
	v_readfirstlane_b32 s40, v116
	v_readfirstlane_b32 s41, v117
	v_readfirstlane_b32 s42, v118
	v_readfirstlane_b32 s43, v119
	v_readfirstlane_b32 s44, v120
	v_readfirstlane_b32 s45, v121
	v_readfirstlane_b32 s46, v122
	v_readfirstlane_b32 s47, v123
	v_writelane_b32 v249, s40, 24
	v_writelane_b32 v249, s41, 25
	v_writelane_b32 v249, s42, 26
	v_writelane_b32 v249, s43, 27
	v_writelane_b32 v249, s44, 28
	v_writelane_b32 v249, s45, 29
	v_writelane_b32 v249, s46, 30
	v_writelane_b32 v249, s47, 31
	v_readfirstlane_b32 s40, v124
	v_readfirstlane_b32 s41, v125
	v_readfirstlane_b32 s42, v126
	v_readfirstlane_b32 s43, v127
	v_readfirstlane_b32 s44, v128
	v_readfirstlane_b32 s45, v129
	v_readfirstlane_b32 s46, v130
	v_readfirstlane_b32 s47, v131
	v_writelane_b32 v249, s40, 32
	v_writelane_b32 v249, s41, 33
	v_writelane_b32 v249, s42, 34
	v_writelane_b32 v249, s43, 35
	v_writelane_b32 v249, s44, 36
	v_writelane_b32 v249, s45, 37
	v_writelane_b32 v249, s46, 38
	v_writelane_b32 v249, s47, 39
	v_readfirstlane_b32 s40, v132
	v_readfirstlane_b32 s41, v133
	s_nop 1
	v_writelane_b32 v249, s40, 40
	v_writelane_b32 v249, s41, 41
	v_readfirstlane_b32 s100, v90
	v_readfirstlane_b32 s101, v91
	v_lshrrev_b32_e32 v238, 4, v172
	v_and_b32_e32 v238, 7, v238
	v_and_b32_e32 v239, 7, v172
	v_xor_b32_e32 v238, v238, v239
	v_lshlrev_b32_e32 v238, 4, v238
	v_lshrrev_b32_e32 v239, 3, v172
	v_lshl_or_b32 v228, v239, 11, v238
	v_and_b32_e32 v238, 15, v172
	v_lshrrev_b32_e32 v239, 1, v238
	v_and_b32_e32 v239, 7, v239
	v_bfe_u32 v240, v172, 4, 2
	v_xor_b32_e32 v239, v239, v240
	v_lshlrev_b32_e32 v239, 4, v239
	v_and_b32_e32 v240, 7, v238
	v_lshl_or_b32 v239, v240, 7, v239
	v_lshrrev_b32_e32 v240, 3, v238
	v_lshl_or_b32 v239, v240, 10, v239
	v_lshrrev_b32_e32 v240, 7, v172
	v_lshl_or_b32 v231, v240, 14, v239
	v_bfe_u32 v240, v172, 6, 1
	v_lshl_or_b32 v232, v240, 13, v239
	v_add_u32_e32 v232, 0x10000, v232
	v_xor_b32_e32 v235, 64, v231
	v_xor_b32_e32 v236, 64, v232
	v_readfirstlane_b32 s46, v172
	s_nop 3
	s_lshr_b32 s46, s46, 6
	s_lshl_b32 s46, s46, 10
	v_lshrrev_b32_e32 v238, 7, v172
	v_and_b32_e32 v239, 15, v172
	v_lshl_or_b32 v238, v238, 7, v239
	v_bfe_u32 v239, v172, 6, 1
	v_bfe_u32 v240, v172, 4, 2
	v_lshlrev_b32_e32 v240, 3, v240
	v_lshl_or_b32 v239, v239, 6, v240
	s_movk_i32 s45, 0x1600
	v_mad_u32_u24 v234, v238, s45, v239
	s_mov_b32 s44, s39
.Lfu_tile:
	s_cmp_ge_u32 s44, s23
	s_cbranch_scc1 .Lfu_exit
	s_and_saveexec_b64 s[48:49], s[62:63]
	s_cbranch_execz .Lfu_tk0
	v_mov_b32_e32 v0, 1
	global_atomic_add v233, v1, v0, s[36:37] sc0
;     ...
; #pragma unroll
;   for (int i = 0; i < 4; ++i) __builtin_amdgcn_global_load_lds((const unsigned*)(ag + (size_t)(32 * i) * lda), (unsigned*)(smem + i * 4096 + o0), 16, 0, 0);
; #pragma unroll
;   for (int i = 0; i < NT; ++i) __builtin_amdgcn_global_load_lds((const unsigned*)(bg + (size_t)((i & 1) * bs1 + (i >> 1) * bs2) * ldb), (unsigned*)(smem + 16384 + i * 4096 + o0), 16, 0, 0);
;   asm volatile("s_waitcnt vmcnt(0)" ::: "memory");
;   __syncthreads();
;   for (int kt = 0; kt < nk; ++kt) {
;     const int cur = (kt & 1) * 32768, nxt = 32768 - cur;
;     if (kt + 1 < nk) {
; #pragma unroll
;       for (int i = 0; i < 4; ++i)
;         __builtin_amdgcn_global_load_lds((const unsigned*)(A8 + (size_t)(kt + 1) * 128 + aoff[i]), (unsigned*)(smem + nxt + i * 4096 + wbase), 16, 0, 0);
; #pragma unroll
;       for (int i = 0; i < NT; ++i)
;         __builtin_amdgcn_global_load_lds((const unsigned*)(B8 + (size_t)(kt + 1) * 128 + boff[i]), (unsigned*)(smem + nxt + 16384 + i * 4096 + wbase), 16, 0, 0);
;     }
;     __builtin_amdgcn_sched_barrier(0);
;     if (LEAN) {
; #pragma unroll
;       for (int ks = 0; ks < 2; ++ks) {
;         bf16x8 af[4], bfr[NT];
; #pragma unroll
;         for (int m = 0; m < 4; ++m) af[m] = *(const bf16x8*)(smem + cur + ((abase + m * 2048) ^ (ks * 64)));
; #pragma unroll
;         for (int n = 0; n < NT; ++n) bfr[n] = *(const bf16x8*)(smem + cur + ((bbase + n * 2048) ^ (ks * 64)));
;         __builtin_amdgcn_s_setprio(1);
; #pragma unroll
;         for (int m = 0; m < 4; ++m)
; #pragma unroll
;           for (int n = 0; n < NT; ++n) acc[m][n] = __builtin_amdgcn_mfma_f32_16x16x32_bf16(bfr[n], af[m], acc[m][n], 0, 0, 0);
.Lfu_tk0:
	s_or_b64 exec, exec, s[48:49]
	s_mul_i32 s45, s44, 2979
	s_lshr_b32 s45, s45, 16
	s_mul_i32 s48, s45, 22
	s_sub_i32 s48, s44, s48
	s_lshl_b32 s45, s45, 3
	s_add_i32 s45, s45, s72
	s_lshr_b32 s47, s45, 2
	s_and_b32 s45, s45, 3
	s_cmp_ge_u32 s48, 11
	s_cselect_b32 s49, 1, 0
	s_cselect_b32 s98, 11, 0
	s_sub_i32 s48, s48, s98
	s_lshl_b32 s47, s47, 1
	s_add_i32 s47, s47, s49
	s_mul_i32 s45, s45, 11
	s_add_i32 s98, s45, s48
	s_lshl_b32 s45, s47, 19
	s_add_u32 s40, s100, s45
	s_addc_u32 s41, s101, 0
	s_add_u32 s40, s40, 0x4380000
	s_addc_u32 s41, s41, 0
	v_readlane_b32 s45, v249, 42
	s_lshl_b32 s48, s98, 18
	s_add_u32 s42, s100, s48
	s_addc_u32 s43, s101, 0
	s_add_u32 s42, s42, s45
	s_addc_u32 s43, s43, 0
	s_add_i32 m0, s46, 0x0
	s_nop 0
	global_load_lds_dwordx4 v228, s[40:41]
	v_add_u32_e32 v230, 0x10000, v228
	s_add_i32 m0, s46, 0x1000
	s_nop 0
	global_load_lds_dwordx4 v230, s[40:41]
	v_add_u32_e32 v230, 0x20000, v228
	s_add_i32 m0, s46, 0x2000
	s_nop 0
	global_load_lds_dwordx4 v230, s[40:41]
	v_add_u32_e32 v230, 0x30000, v228
	s_add_i32 m0, s46, 0x3000
	s_nop 0
	global_load_lds_dwordx4 v230, s[40:41]
	v_add_u32_e32 v230, 0x40000, v228
	s_add_i32 m0, s46, 0x4000
	s_nop 0
	global_load_lds_dwordx4 v230, s[40:41]
	v_add_u32_e32 v230, 0x50000, v228
	s_add_i32 m0, s46, 0x5000
	s_nop 0
	global_load_lds_dwordx4 v230, s[40:41]
	v_add_u32_e32 v230, 0x60000, v228
	s_add_i32 m0, s46, 0x6000
	s_nop 0
	global_load_lds_dwordx4 v230, s[40:41]
	v_add_u32_e32 v230, 0x70000, v228
	s_add_i32 m0, s46, 0x7000
	s_nop 0
	global_load_lds_dwordx4 v230, s[40:41]
	s_add_i32 m0, s46, 0x10000
	s_nop 0
	global_load_lds_dwordx4 v228, s[42:43]
	v_add_u32_e32 v230, 0x10000, v228
	s_add_i32 m0, s46, 0x11000
	s_nop 0
	global_load_lds_dwordx4 v230, s[42:43]
	v_add_u32_e32 v230, 0x20000, v228
	s_add_i32 m0, s46, 0x12000
	s_nop 0
	global_load_lds_dwordx4 v230, s[42:43]
	v_add_u32_e32 v230, 0x30000, v228
	s_add_i32 m0, s46, 0x13000
	s_nop 0
	global_load_lds_dwordx4 v230, s[42:43]
	v_mov_b64_e32 v[2:3], 0
	v_mov_b64_e32 v[4:5], 0
	v_mov_b64_e32 v[6:7], 0
	v_mov_b64_e32 v[8:9], 0
	v_mov_b64_e32 v[10:11], 0
	v_mov_b64_e32 v[12:13], 0
	v_mov_b64_e32 v[14:15], 0
	v_mov_b64_e32 v[16:17], 0
	v_mov_b64_e32 v[18:19], 0
	v_mov_b64_e32 v[20:21], 0
	v_mov_b64_e32 v[22:23], 0
	v_mov_b64_e32 v[24:25], 0
	v_mov_b64_e32 v[26:27], 0
	v_mov_b64_e32 v[28:29], 0
	v_mov_b64_e32 v[30:31], 0
	v_mov_b64_e32 v[32:33], 0
	v_mov_b64_e32 v[34:35], 0
	v_mov_b64_e32 v[36:37], 0
	v_mov_b64_e32 v[38:39], 0
	v_mov_b64_e32 v[40:41], 0
	v_mov_b64_e32 v[42:43], 0
	v_mov_b64_e32 v[44:45], 0
	v_mov_b64_e32 v[46:47], 0
	v_mov_b64_e32 v[48:49], 0
	v_mov_b64_e32 v[50:51], 0
	v_mov_b64_e32 v[52:53], 0
	v_mov_b64_e32 v[54:55], 0
	v_mov_b64_e32 v[56:57], 0
	v_mov_b64_e32 v[58:59], 0
	v_mov_b64_e32 v[60:61], 0
	v_mov_b64_e32 v[62:63], 0
	v_mov_b64_e32 v[64:65], 0
	v_mov_b64_e32 v[66:67], 0
	v_mov_b64_e32 v[68:69], 0
	v_mov_b64_e32 v[70:71], 0
	v_mov_b64_e32 v[72:73], 0
	v_mov_b64_e32 v[74:75], 0
	v_mov_b64_e32 v[76:77], 0
	v_mov_b64_e32 v[78:79], 0
	v_mov_b64_e32 v[80:81], 0
	v_mov_b64_e32 v[82:83], 0
	v_mov_b64_e32 v[84:85], 0
	v_mov_b64_e32 v[86:87], 0
	v_mov_b64_e32 v[88:89], 0
	v_mov_b64_e32 v[92:93], 0
	v_mov_b64_e32 v[94:95], 0
	v_mov_b64_e32 v[96:97], 0
	v_mov_b64_e32 v[98:99], 0
	v_mov_b64_e32 v[100:101], 0
	v_mov_b64_e32 v[102:103], 0
	v_mov_b64_e32 v[104:105], 0
	v_mov_b64_e32 v[106:107], 0
	v_mov_b64_e32 v[108:109], 0
	v_mov_b64_e32 v[110:111], 0
	v_mov_b64_e32 v[112:113], 0
	v_mov_b64_e32 v[114:115], 0
	v_mov_b64_e32 v[116:117], 0
	v_mov_b64_e32 v[118:119], 0
	v_mov_b64_e32 v[120:121], 0
	v_mov_b64_e32 v[122:123], 0
	v_mov_b64_e32 v[124:125], 0
	v_mov_b64_e32 v[126:127], 0
	v_mov_b64_e32 v[128:129], 0
	v_mov_b64_e32 v[130:131], 0
	s_waitcnt vmcnt(0)
	s_barrier
	s_mov_b32 s45, 7
.Lfu_kloop:
	ds_read_b128 v[136:139], v232
	ds_read_b128 v[140:143], v232 offset:2048
	ds_read_b128 v[144:147], v232 offset:4096
	ds_read_b128 v[148:151], v232 offset:6144
	ds_read_b128 v[196:199], v231
	ds_read_b128 v[200:203], v231 offset:2048
	ds_read_b128 v[204:207], v231 offset:4096
	ds_read_b128 v[208:211], v231 offset:6144
	ds_read_b128 v[152:155], v236
	ds_read_b128 v[156:159], v236 offset:2048
	ds_read_b128 v[160:163], v236 offset:4096
	ds_read_b128 v[164:167], v236 offset:6144
	ds_read_b128 v[212:215], v231 offset:8192
	ds_read_b128 v[216:219], v231 offset:10240
	ds_read_b128 v[220:223], v231 offset:12288
	ds_read_b128 v[224:227], v231 offset:14336
	s_setprio 1
	s_waitcnt lgkmcnt(8)
	v_mfma_f32_16x16x32_bf16 v[2:5], v[136:139], v[196:199], v[2:5]
	v_mfma_f32_16x16x32_bf16 v[6:9], v[140:143], v[196:199], v[6:9]
	v_mfma_f32_16x16x32_bf16 v[10:13], v[144:147], v[196:199], v[10:13]
	v_mfma_f32_16x16x32_bf16 v[14:17], v[148:151], v[196:199], v[14:17]
	v_mfma_f32_16x16x32_bf16 v[18:21], v[136:139], v[200:203], v[18:21]
	v_mfma_f32_16x16x32_bf16 v[22:25], v[140:143], v[200:203], v[22:25]
	v_mfma_f32_16x16x32_bf16 v[26:29], v[144:147], v[200:203], v[26:29]
	v_mfma_f32_16x16x32_bf16 v[30:33], v[148:151], v[200:203], v[30:33]
	v_mfma_f32_16x16x32_bf16 v[34:37], v[136:139], v[204:207], v[34:37]
	v_mfma_f32_16x16x32_bf16 v[38:41], v[140:143], v[204:207], v[38:41]
	v_mfma_f32_16x16x32_bf16 v[42:45], v[144:147], v[204:207], v[42:45]
	v_mfma_f32_16x16x32_bf16 v[46:49], v[148:151], v[204:207], v[46:49]
	v_mfma_f32_16x16x32_bf16 v[50:53], v[136:139], v[208:211], v[50:53]
	v_mfma_f32_16x16x32_bf16 v[54:57], v[140:143], v[208:211], v[54:57]
	v_mfma_f32_16x16x32_bf16 v[58:61], v[144:147], v[208:211], v[58:61]
	v_mfma_f32_16x16x32_bf16 v[62:65], v[148:151], v[208:211], v[62:65]
	s_waitcnt lgkmcnt(0)
	s_barrier
;     ...
;   for (int kt = 0; kt < nk; ++kt) {
;     const int cur = (kt & 1) * 32768, nxt = 32768 - cur;
;     if (kt + 1 < nk) {
; #pragma unroll
;       for (int i = 0; i < 4; ++i)
;         __builtin_amdgcn_global_load_lds((const unsigned*)(A8 + (size_t)(kt + 1) * 128 + aoff[i]), (unsigned*)(smem + nxt + i * 4096 + wbase), 16, 0, 0);
; #pragma unroll
;       for (int i = 0; i < NT; ++i)
;         __builtin_amdgcn_global_load_lds((const unsigned*)(B8 + (size_t)(kt + 1) * 128 + boff[i]), (unsigned*)(smem + nxt + 16384 + i * 4096 + wbase), 16, 0, 0);
;     }
;     __builtin_amdgcn_sched_barrier(0);
;     if (LEAN) {
; #pragma unroll
;       for (int ks = 0; ks < 2; ++ks) {
;         bf16x8 af[4], bfr[NT];
; #pragma unroll
;         for (int m = 0; m < 4; ++m) af[m] = *(const bf16x8*)(smem + cur + ((abase + m * 2048) ^ (ks * 64)));
; #pragma unroll
;         for (int n = 0; n < NT; ++n) bfr[n] = *(const bf16x8*)(smem + cur + ((bbase + n * 2048) ^ (ks * 64)));
;         __builtin_amdgcn_s_setprio(1);
; #pragma unroll
;         for (int m = 0; m < 4; ++m)
; #pragma unroll
;           for (int n = 0; n < NT; ++n) acc[m][n] = __builtin_amdgcn_mfma_f32_16x16x32_bf16(bfr[n], af[m], acc[m][n], 0, 0, 0);
;         __builtin_amdgcn_s_setprio(0);
;       }
	s_add_u32 s40, s40, 0x80
	s_addc_u32 s41, s41, 0
	s_add_u32 s42, s42, 0x80
	s_addc_u32 s43, s43, 0
	ds_read_b128 v[196:199], v235
	ds_read_b128 v[200:203], v235 offset:2048
	ds_read_b128 v[204:207], v235 offset:4096
	ds_read_b128 v[208:211], v235 offset:6144
	s_add_i32 m0, s46, 0x8000
	v_mfma_f32_16x16x32_bf16 v[66:69], v[136:139], v[212:215], v[66:69]
	global_load_lds_dwordx4 v228, s[40:41]
	v_add_u32_e32 v230, 0x10000, v228
	s_add_i32 m0, s46, 0x9000
	v_mfma_f32_16x16x32_bf16 v[70:73], v[140:143], v[212:215], v[70:73]
	global_load_lds_dwordx4 v230, s[40:41]
	v_add_u32_e32 v230, 0x20000, v228
	s_add_i32 m0, s46, 0xa000
	v_mfma_f32_16x16x32_bf16 v[74:77], v[144:147], v[212:215], v[74:77]
	global_load_lds_dwordx4 v230, s[40:41]
	v_add_u32_e32 v230, 0x30000, v228
	s_add_i32 m0, s46, 0xb000
	v_mfma_f32_16x16x32_bf16 v[78:81], v[148:151], v[212:215], v[78:81]
	global_load_lds_dwordx4 v230, s[40:41]
	v_add_u32_e32 v230, 0x40000, v228
	s_add_i32 m0, s46, 0xc000
	v_mfma_f32_16x16x32_bf16 v[82:85], v[136:139], v[216:219], v[82:85]
	global_load_lds_dwordx4 v230, s[40:41]
	v_add_u32_e32 v230, 0x50000, v228
	s_add_i32 m0, s46, 0xd000
	v_mfma_f32_16x16x32_bf16 v[86:89], v[140:143], v[216:219], v[86:89]
	global_load_lds_dwordx4 v230, s[40:41]
	v_add_u32_e32 v230, 0x60000, v228
	s_add_i32 m0, s46, 0xe000
	v_mfma_f32_16x16x32_bf16 v[92:95], v[144:147], v[216:219], v[92:95]
	global_load_lds_dwordx4 v230, s[40:41]
	v_add_u32_e32 v230, 0x70000, v228
	s_add_i32 m0, s46, 0xf000
	v_mfma_f32_16x16x32_bf16 v[96:99], v[148:151], v[216:219], v[96:99]
	global_load_lds_dwordx4 v230, s[40:41]
	s_add_i32 m0, s46, 0x10000
	v_mfma_f32_16x16x32_bf16 v[100:103], v[136:139], v[220:223], v[100:103]
	global_load_lds_dwordx4 v228, s[42:43]
	v_add_u32_e32 v230, 0x10000, v228
	s_add_i32 m0, s46, 0x11000
	v_mfma_f32_16x16x32_bf16 v[104:107], v[140:143], v[220:223], v[104:107]
	global_load_lds_dwordx4 v230, s[42:43]
	v_add_u32_e32 v230, 0x20000, v228
	s_add_i32 m0, s46, 0x12000
	v_mfma_f32_16x16x32_bf16 v[108:111], v[144:147], v[220:223], v[108:111]
	global_load_lds_dwordx4 v230, s[42:43]
	v_add_u32_e32 v230, 0x30000, v228
	s_add_i32 m0, s46, 0x13000
	v_mfma_f32_16x16x32_bf16 v[112:115], v[148:151], v[220:223], v[112:115]
	global_load_lds_dwordx4 v230, s[42:43]
	v_mfma_f32_16x16x32_bf16 v[116:119], v[136:139], v[224:227], v[116:119]
	v_mfma_f32_16x16x32_bf16 v[120:123], v[140:143], v[224:227], v[120:123]
	v_mfma_f32_16x16x32_bf16 v[124:127], v[144:147], v[224:227], v[124:127]
	v_mfma_f32_16x16x32_bf16 v[128:131], v[148:151], v[224:227], v[128:131]
	ds_read_b128 v[212:215], v235 offset:8192
	ds_read_b128 v[216:219], v235 offset:10240
	ds_read_b128 v[220:223], v235 offset:12288
	ds_read_b128 v[224:227], v235 offset:14336
	s_waitcnt lgkmcnt(4)
	v_mfma_f32_16x16x32_bf16 v[2:5], v[152:155], v[196:199], v[2:5]
	v_mfma_f32_16x16x32_bf16 v[6:9], v[156:159], v[196:199], v[6:9]
	v_mfma_f32_16x16x32_bf16 v[10:13], v[160:163], v[196:199], v[10:13]
	v_mfma_f32_16x16x32_bf16 v[14:17], v[164:167], v[196:199], v[14:17]
	v_mfma_f32_16x16x32_bf16 v[18:21], v[152:155], v[200:203], v[18:21]
	v_mfma_f32_16x16x32_bf16 v[22:25], v[156:159], v[200:203], v[22:25]
	v_mfma_f32_16x16x32_bf16 v[26:29], v[160:163], v[200:203], v[26:29]
	v_mfma_f32_16x16x32_bf16 v[30:33], v[164:167], v[200:203], v[30:33]
	v_mfma_f32_16x16x32_bf16 v[34:37], v[152:155], v[204:207], v[34:37]
	v_mfma_f32_16x16x32_bf16 v[38:41], v[156:159], v[204:207], v[38:41]
	v_mfma_f32_16x16x32_bf16 v[42:45], v[160:163], v[204:207], v[42:45]
	v_mfma_f32_16x16x32_bf16 v[46:49], v[164:167], v[204:207], v[46:49]
	v_mfma_f32_16x16x32_bf16 v[50:53], v[152:155], v[208:211], v[50:53]
	v_mfma_f32_16x16x32_bf16 v[54:57], v[156:159], v[208:211], v[54:57]
	v_mfma_f32_16x16x32_bf16 v[58:61], v[160:163], v[208:211], v[58:61]
	v_mfma_f32_16x16x32_bf16 v[62:65], v[164:167], v[208:211], v[62:65]
	s_waitcnt lgkmcnt(0)
	v_mfma_f32_16x16x32_bf16 v[66:69], v[152:155], v[212:215], v[66:69]
	v_mfma_f32_16x16x32_bf16 v[70:73], v[156:159], v[212:215], v[70:73]
	v_mfma_f32_16x16x32_bf16 v[74:77], v[160:163], v[212:215], v[74:77]
	v_mfma_f32_16x16x32_bf16 v[78:81], v[164:167], v[212:215], v[78:81]
	v_mfma_f32_16x16x32_bf16 v[82:85], v[152:155], v[216:219], v[82:85]
	v_mfma_f32_16x16x32_bf16 v[86:89], v[156:159], v[216:219], v[86:89]
	v_mfma_f32_16x16x32_bf16 v[92:95], v[160:163], v[216:219], v[92:95]
	v_mfma_f32_16x16x32_bf16 v[96:99], v[164:167], v[216:219], v[96:99]
	v_mfma_f32_16x16x32_bf16 v[100:103], v[152:155], v[220:223], v[100:103]
	v_mfma_f32_16x16x32_bf16 v[104:107], v[156:159], v[220:223], v[104:107]
	v_mfma_f32_16x16x32_bf16 v[108:111], v[160:163], v[220:223], v[108:111]
	v_mfma_f32_16x16x32_bf16 v[112:115], v[164:167], v[220:223], v[112:115]
	v_mfma_f32_16x16x32_bf16 v[116:119], v[152:155], v[224:227], v[116:119]
	v_mfma_f32_16x16x32_bf16 v[120:123], v[156:159], v[224:227], v[120:123]
	v_mfma_f32_16x16x32_bf16 v[124:127], v[160:163], v[224:227], v[124:127]
	v_mfma_f32_16x16x32_bf16 v[128:131], v[164:167], v[224:227], v[128:131]
	s_setprio 0
	s_waitcnt vmcnt(0)
	s_barrier
;     ...
;   for (int kt = 0; kt < nk; ++kt) {
;     const int cur = (kt & 1) * 32768, nxt = 32768 - cur;
;     if (kt + 1 < nk) {
; #pragma unroll
;       for (int i = 0; i < 4; ++i)
;         __builtin_amdgcn_global_load_lds((const unsigned*)(A8 + (size_t)(kt + 1) * 128 + aoff[i]), (unsigned*)(smem + nxt + i * 4096 + wbase), 16, 0, 0);
; #pragma unroll
;       for (int i = 0; i < NT; ++i)
;         __builtin_amdgcn_global_load_lds((const unsigned*)(B8 + (size_t)(kt + 1) * 128 + boff[i]), (unsigned*)(smem + nxt + 16384 + i * 4096 + wbase), 16, 0, 0);
;     }
;     __builtin_amdgcn_sched_barrier(0);
;     if (LEAN) {
; #pragma unroll
;       for (int ks = 0; ks < 2; ++ks) {
;         bf16x8 af[4], bfr[NT];
; #pragma unroll
;         for (int m = 0; m < 4; ++m) af[m] = *(const bf16x8*)(smem + cur + ((abase + m * 2048) ^ (ks * 64)));
; #pragma unroll
;         for (int n = 0; n < NT; ++n) bfr[n] = *(const bf16x8*)(smem + cur + ((bbase + n * 2048) ^ (ks * 64)));
;         __builtin_amdgcn_s_setprio(1);
; #pragma unroll
;         for (int m = 0; m < 4; ++m)
; #pragma unroll
;           for (int n = 0; n < NT; ++n) acc[m][n] = __builtin_amdgcn_mfma_f32_16x16x32_bf16(bfr[n], af[m], acc[m][n], 0, 0, 0);
;         __builtin_amdgcn_s_setprio(0);
;       }
	ds_read_b128 v[136:139], v232
	ds_read_b128 v[140:143], v232 offset:2048
	ds_read_b128 v[144:147], v232 offset:4096
	ds_read_b128 v[148:151], v232 offset:6144
	ds_read_b128 v[196:199], v231 offset:32768
	ds_read_b128 v[200:203], v231 offset:34816
	ds_read_b128 v[204:207], v231 offset:36864
	ds_read_b128 v[208:211], v231 offset:38912
	ds_read_b128 v[152:155], v236
	ds_read_b128 v[156:159], v236 offset:2048
	ds_read_b128 v[160:163], v236 offset:4096
	ds_read_b128 v[164:167], v236 offset:6144
	ds_read_b128 v[212:215], v231 offset:40960
	ds_read_b128 v[216:219], v231 offset:43008
	ds_read_b128 v[220:223], v231 offset:45056
	ds_read_b128 v[224:227], v231 offset:47104
	s_setprio 1
	s_waitcnt lgkmcnt(8)
	v_mfma_f32_16x16x32_bf16 v[2:5], v[136:139], v[196:199], v[2:5]
	v_mfma_f32_16x16x32_bf16 v[6:9], v[140:143], v[196:199], v[6:9]
	v_mfma_f32_16x16x32_bf16 v[10:13], v[144:147], v[196:199], v[10:13]
	v_mfma_f32_16x16x32_bf16 v[14:17], v[148:151], v[196:199], v[14:17]
	v_mfma_f32_16x16x32_bf16 v[18:21], v[136:139], v[200:203], v[18:21]
	v_mfma_f32_16x16x32_bf16 v[22:25], v[140:143], v[200:203], v[22:25]
	v_mfma_f32_16x16x32_bf16 v[26:29], v[144:147], v[200:203], v[26:29]
	v_mfma_f32_16x16x32_bf16 v[30:33], v[148:151], v[200:203], v[30:33]
	v_mfma_f32_16x16x32_bf16 v[34:37], v[136:139], v[204:207], v[34:37]
	v_mfma_f32_16x16x32_bf16 v[38:41], v[140:143], v[204:207], v[38:41]
	v_mfma_f32_16x16x32_bf16 v[42:45], v[144:147], v[204:207], v[42:45]
	v_mfma_f32_16x16x32_bf16 v[46:49], v[148:151], v[204:207], v[46:49]
	v_mfma_f32_16x16x32_bf16 v[50:53], v[136:139], v[208:211], v[50:53]
	v_mfma_f32_16x16x32_bf16 v[54:57], v[140:143], v[208:211], v[54:57]
	v_mfma_f32_16x16x32_bf16 v[58:61], v[144:147], v[208:211], v[58:61]
	v_mfma_f32_16x16x32_bf16 v[62:65], v[148:151], v[208:211], v[62:65]
	s_waitcnt lgkmcnt(0)
	s_barrier
	s_add_u32 s40, s40, 0x80
	s_addc_u32 s41, s41, 0
	s_add_u32 s42, s42, 0x80
	s_addc_u32 s43, s43, 0
	ds_read_b128 v[196:199], v235 offset:32768
	ds_read_b128 v[200:203], v235 offset:34816
	ds_read_b128 v[204:207], v235 offset:36864
	ds_read_b128 v[208:211], v235 offset:38912
	s_add_i32 m0, s46, 0x0
	v_mfma_f32_16x16x32_bf16 v[66:69], v[136:139], v[212:215], v[66:69]
	global_load_lds_dwordx4 v228, s[40:41]
	v_add_u32_e32 v230, 0x10000, v228
	s_add_i32 m0, s46, 0x1000
	v_mfma_f32_16x16x32_bf16 v[70:73], v[140:143], v[212:215], v[70:73]
	global_load_lds_dwordx4 v230, s[40:41]
	v_add_u32_e32 v230, 0x20000, v228
	s_add_i32 m0, s46, 0x2000
	v_mfma_f32_16x16x32_bf16 v[74:77], v[144:147], v[212:215], v[74:77]
	global_load_lds_dwordx4 v230, s[40:41]
	v_add_u32_e32 v230, 0x30000, v228
	s_add_i32 m0, s46, 0x3000
	v_mfma_f32_16x16x32_bf16 v[78:81], v[148:151], v[212:215], v[78:81]
	global_load_lds_dwordx4 v230, s[40:41]
	v_add_u32_e32 v230, 0x40000, v228
	s_add_i32 m0, s46, 0x4000
	v_mfma_f32_16x16x32_bf16 v[82:85], v[136:139], v[216:219], v[82:85]
	global_load_lds_dwordx4 v230, s[40:41]
	v_add_u32_e32 v230, 0x50000, v228
	s_add_i32 m0, s46, 0x5000
	v_mfma_f32_16x16x32_bf16 v[86:89], v[140:143], v[216:219], v[86:89]
	global_load_lds_dwordx4 v230, s[40:41]
	v_add_u32_e32 v230, 0x60000, v228
	s_add_i32 m0, s46, 0x6000
	v_mfma_f32_16x16x32_bf16 v[92:95], v[144:147], v[216:219], v[92:95]
	global_load_lds_dwordx4 v230, s[40:41]
	v_add_u32_e32 v230, 0x70000, v228
	s_add_i32 m0, s46, 0x7000
	v_mfma_f32_16x16x32_bf16 v[96:99], v[148:151], v[216:219], v[96:99]
	global_load_lds_dwordx4 v230, s[40:41]
	s_add_i32 m0, s46, 0x10000
	v_mfma_f32_16x16x32_bf16 v[100:103], v[136:139], v[220:223], v[100:103]
	global_load_lds_dwordx4 v228, s[42:43]
	v_add_u32_e32 v230, 0x10000, v228
	s_add_i32 m0, s46, 0x11000
	v_mfma_f32_16x16x32_bf16 v[104:107], v[140:143], v[220:223], v[104:107]
	global_load_lds_dwordx4 v230, s[42:43]
	v_add_u32_e32 v230, 0x20000, v228
	s_add_i32 m0, s46, 0x12000
	v_mfma_f32_16x16x32_bf16 v[108:111], v[144:147], v[220:223], v[108:111]
	global_load_lds_dwordx4 v230, s[42:43]
	v_add_u32_e32 v230, 0x30000, v228
	s_add_i32 m0, s46, 0x13000
	v_mfma_f32_16x16x32_bf16 v[112:115], v[148:151], v[220:223], v[112:115]
	global_load_lds_dwordx4 v230, s[42:43]
	v_mfma_f32_16x16x32_bf16 v[116:119], v[136:139], v[224:227], v[116:119]
	v_mfma_f32_16x16x32_bf16 v[120:123], v[140:143], v[224:227], v[120:123]
	v_mfma_f32_16x16x32_bf16 v[124:127], v[144:147], v[224:227], v[124:127]
	v_mfma_f32_16x16x32_bf16 v[128:131], v[148:151], v[224:227], v[128:131]
	ds_read_b128 v[212:215], v235 offset:40960
	ds_read_b128 v[216:219], v235 offset:43008
	ds_read_b128 v[220:223], v235 offset:45056
	ds_read_b128 v[224:227], v235 offset:47104
	s_waitcnt lgkmcnt(4)
	v_mfma_f32_16x16x32_bf16 v[2:5], v[152:155], v[196:199], v[2:5]
	v_mfma_f32_16x16x32_bf16 v[6:9], v[156:159], v[196:199], v[6:9]
	v_mfma_f32_16x16x32_bf16 v[10:13], v[160:163], v[196:199], v[10:13]
	v_mfma_f32_16x16x32_bf16 v[14:17], v[164:167], v[196:199], v[14:17]
	v_mfma_f32_16x16x32_bf16 v[18:21], v[152:155], v[200:203], v[18:21]
	v_mfma_f32_16x16x32_bf16 v[22:25], v[156:159], v[200:203], v[22:25]
	v_mfma_f32_16x16x32_bf16 v[26:29], v[160:163], v[200:203], v[26:29]
	v_mfma_f32_16x16x32_bf16 v[30:33], v[164:167], v[200:203], v[30:33]
	v_mfma_f32_16x16x32_bf16 v[34:37], v[152:155], v[204:207], v[34:37]
	v_mfma_f32_16x16x32_bf16 v[38:41], v[156:159], v[204:207], v[38:41]
	v_mfma_f32_16x16x32_bf16 v[42:45], v[160:163], v[204:207], v[42:45]
	v_mfma_f32_16x16x32_bf16 v[46:49], v[164:167], v[204:207], v[46:49]
	v_mfma_f32_16x16x32_bf16 v[50:53], v[152:155], v[208:211], v[50:53]
	v_mfma_f32_16x16x32_bf16 v[54:57], v[156:159], v[208:211], v[54:57]
	v_mfma_f32_16x16x32_bf16 v[58:61], v[160:163], v[208:211], v[58:61]
	v_mfma_f32_16x16x32_bf16 v[62:65], v[164:167], v[208:211], v[62:65]
	s_waitcnt lgkmcnt(0)
	v_mfma_f32_16x16x32_bf16 v[66:69], v[152:155], v[212:215], v[66:69]
	v_mfma_f32_16x16x32_bf16 v[70:73], v[156:159], v[212:215], v[70:73]
	v_mfma_f32_16x16x32_bf16 v[74:77], v[160:163], v[212:215], v[74:77]
	v_mfma_f32_16x16x32_bf16 v[78:81], v[164:167], v[212:215], v[78:81]
	v_mfma_f32_16x16x32_bf16 v[82:85], v[152:155], v[216:219], v[82:85]
	v_mfma_f32_16x16x32_bf16 v[86:89], v[156:159], v[216:219], v[86:89]
	v_mfma_f32_16x16x32_bf16 v[92:95], v[160:163], v[216:219], v[92:95]
	v_mfma_f32_16x16x32_bf16 v[96:99], v[164:167], v[216:219], v[96:99]
	v_mfma_f32_16x16x32_bf16 v[100:103], v[152:155], v[220:223], v[100:103]
	v_mfma_f32_16x16x32_bf16 v[104:107], v[156:159], v[220:223], v[104:107]
	v_mfma_f32_16x16x32_bf16 v[108:111], v[160:163], v[220:223], v[108:111]
	v_mfma_f32_16x16x32_bf16 v[112:115], v[164:167], v[220:223], v[112:115]
	v_mfma_f32_16x16x32_bf16 v[116:119], v[152:155], v[224:227], v[116:119]
	v_mfma_f32_16x16x32_bf16 v[120:123], v[156:159], v[224:227], v[120:123]
	v_mfma_f32_16x16x32_bf16 v[124:127], v[160:163], v[224:227], v[124:127]
	v_mfma_f32_16x16x32_bf16 v[128:131], v[164:167], v[224:227], v[128:131]
	s_setprio 0
	s_waitcnt vmcnt(0)
	s_barrier
;     ...
;   for (int kt = 0; kt < nk; ++kt) {
;     const int cur = (kt & 1) * 32768, nxt = 32768 - cur;
;     if (kt + 1 < nk) {
; #pragma unroll
;       for (int i = 0; i < 4; ++i)
;         __builtin_amdgcn_global_load_lds((const unsigned*)(A8 + (size_t)(kt + 1) * 128 + aoff[i]), (unsigned*)(smem + nxt + i * 4096 + wbase), 16, 0, 0);
; #pragma unroll
;       for (int i = 0; i < NT; ++i)
;         __builtin_amdgcn_global_load_lds((const unsigned*)(B8 + (size_t)(kt + 1) * 128 + boff[i]), (unsigned*)(smem + nxt + 16384 + i * 4096 + wbase), 16, 0, 0);
;     }
;     __builtin_amdgcn_sched_barrier(0);
;     if (LEAN) {
; #pragma unroll
;       for (int ks = 0; ks < 2; ++ks) {
;         bf16x8 af[4], bfr[NT];
; #pragma unroll
;         for (int m = 0; m < 4; ++m) af[m] = *(const bf16x8*)(smem + cur + ((abase + m * 2048) ^ (ks * 64)));
; #pragma unroll
;         for (int n = 0; n < NT; ++n) bfr[n] = *(const bf16x8*)(smem + cur + ((bbase + n * 2048) ^ (ks * 64)));
;         __builtin_amdgcn_s_setprio(1);
; #pragma unroll
;         for (int m = 0; m < 4; ++m)
; #pragma unroll
;           for (int n = 0; n < NT; ++n) acc[m][n] = __builtin_amdgcn_mfma_f32_16x16x32_bf16(bfr[n], af[m], acc[m][n], 0, 0, 0);
;         __builtin_amdgcn_s_setprio(0);
;       }
	s_add_i32 s45, s45, -1
	s_cmp_lg_u32 s45, 0
	s_cbranch_scc1 .Lfu_kloop
	ds_read_b128 v[136:139], v232
	ds_read_b128 v[140:143], v232 offset:2048
	ds_read_b128 v[144:147], v232 offset:4096
	ds_read_b128 v[148:151], v232 offset:6144
	ds_read_b128 v[196:199], v231
	ds_read_b128 v[200:203], v231 offset:2048
	ds_read_b128 v[204:207], v231 offset:4096
	ds_read_b128 v[208:211], v231 offset:6144
	ds_read_b128 v[152:155], v236
	ds_read_b128 v[156:159], v236 offset:2048
	ds_read_b128 v[160:163], v236 offset:4096
	ds_read_b128 v[164:167], v236 offset:6144
	ds_read_b128 v[212:215], v231 offset:8192
	ds_read_b128 v[216:219], v231 offset:10240
	ds_read_b128 v[220:223], v231 offset:12288
	ds_read_b128 v[224:227], v231 offset:14336
	s_setprio 1
	s_waitcnt lgkmcnt(8)
	v_mfma_f32_16x16x32_bf16 v[2:5], v[136:139], v[196:199], v[2:5]
	v_mfma_f32_16x16x32_bf16 v[6:9], v[140:143], v[196:199], v[6:9]
	v_mfma_f32_16x16x32_bf16 v[10:13], v[144:147], v[196:199], v[10:13]
	v_mfma_f32_16x16x32_bf16 v[14:17], v[148:151], v[196:199], v[14:17]
	v_mfma_f32_16x16x32_bf16 v[18:21], v[136:139], v[200:203], v[18:21]
	v_mfma_f32_16x16x32_bf16 v[22:25], v[140:143], v[200:203], v[22:25]
	v_mfma_f32_16x16x32_bf16 v[26:29], v[144:147], v[200:203], v[26:29]
	v_mfma_f32_16x16x32_bf16 v[30:33], v[148:151], v[200:203], v[30:33]
	v_mfma_f32_16x16x32_bf16 v[34:37], v[136:139], v[204:207], v[34:37]
	v_mfma_f32_16x16x32_bf16 v[38:41], v[140:143], v[204:207], v[38:41]
	v_mfma_f32_16x16x32_bf16 v[42:45], v[144:147], v[204:207], v[42:45]
	v_mfma_f32_16x16x32_bf16 v[46:49], v[148:151], v[204:207], v[46:49]
	v_mfma_f32_16x16x32_bf16 v[50:53], v[136:139], v[208:211], v[50:53]
	v_mfma_f32_16x16x32_bf16 v[54:57], v[140:143], v[208:211], v[54:57]
	v_mfma_f32_16x16x32_bf16 v[58:61], v[144:147], v[208:211], v[58:61]
	v_mfma_f32_16x16x32_bf16 v[62:65], v[148:151], v[208:211], v[62:65]
	s_waitcnt lgkmcnt(0)
	s_barrier
	s_add_u32 s40, s40, 0x80
	s_addc_u32 s41, s41, 0
	s_add_u32 s42, s42, 0x80
	s_addc_u32 s43, s43, 0
	ds_read_b128 v[196:199], v235
	ds_read_b128 v[200:203], v235 offset:2048
	ds_read_b128 v[204:207], v235 offset:4096
	ds_read_b128 v[208:211], v235 offset:6144
	s_add_i32 m0, s46, 0x8000
	v_mfma_f32_16x16x32_bf16 v[66:69], v[136:139], v[212:215], v[66:69]
	global_load_lds_dwordx4 v228, s[40:41]
	v_add_u32_e32 v230, 0x10000, v228
	s_add_i32 m0, s46, 0x9000
	v_mfma_f32_16x16x32_bf16 v[70:73], v[140:143], v[212:215], v[70:73]
	global_load_lds_dwordx4 v230, s[40:41]
	v_add_u32_e32 v230, 0x20000, v228
	s_add_i32 m0, s46, 0xa000
	v_mfma_f32_16x16x32_bf16 v[74:77], v[144:147], v[212:215], v[74:77]
	global_load_lds_dwordx4 v230, s[40:41]
	v_add_u32_e32 v230, 0x30000, v228
	s_add_i32 m0, s46, 0xb000
	v_mfma_f32_16x16x32_bf16 v[78:81], v[148:151], v[212:215], v[78:81]
	global_load_lds_dwordx4 v230, s[40:41]
	v_add_u32_e32 v230, 0x40000, v228
	s_add_i32 m0, s46, 0xc000
	v_mfma_f32_16x16x32_bf16 v[82:85], v[136:139], v[216:219], v[82:85]
	global_load_lds_dwordx4 v230, s[40:41]
	v_add_u32_e32 v230, 0x50000, v228
	s_add_i32 m0, s46, 0xd000
	v_mfma_f32_16x16x32_bf16 v[86:89], v[140:143], v[216:219], v[86:89]
	global_load_lds_dwordx4 v230, s[40:41]
	v_add_u32_e32 v230, 0x60000, v228
	s_add_i32 m0, s46, 0xe000
	v_mfma_f32_16x16x32_bf16 v[92:95], v[144:147], v[216:219], v[92:95]
	global_load_lds_dwordx4 v230, s[40:41]
	v_add_u32_e32 v230, 0x70000, v228
	s_add_i32 m0, s46, 0xf000
	v_mfma_f32_16x16x32_bf16 v[96:99], v[148:151], v[216:219], v[96:99]
	global_load_lds_dwordx4 v230, s[40:41]
	s_add_i32 m0, s46, 0x10000
	v_mfma_f32_16x16x32_bf16 v[100:103], v[136:139], v[220:223], v[100:103]
	global_load_lds_dwordx4 v228, s[42:43]
	v_add_u32_e32 v230, 0x10000, v228
	s_add_i32 m0, s46, 0x11000
	v_mfma_f32_16x16x32_bf16 v[104:107], v[140:143], v[220:223], v[104:107]
	global_load_lds_dwordx4 v230, s[42:43]
	v_add_u32_e32 v230, 0x20000, v228
	s_add_i32 m0, s46, 0x12000
	v_mfma_f32_16x16x32_bf16 v[108:111], v[144:147], v[220:223], v[108:111]
	global_load_lds_dwordx4 v230, s[42:43]
	v_add_u32_e32 v230, 0x30000, v228
	s_add_i32 m0, s46, 0x13000
	v_mfma_f32_16x16x32_bf16 v[112:115], v[148:151], v[220:223], v[112:115]
	global_load_lds_dwordx4 v230, s[42:43]
	v_mfma_f32_16x16x32_bf16 v[116:119], v[136:139], v[224:227], v[116:119]
	v_mfma_f32_16x16x32_bf16 v[120:123], v[140:143], v[224:227], v[120:123]
	v_mfma_f32_16x16x32_bf16 v[124:127], v[144:147], v[224:227], v[124:127]
	v_mfma_f32_16x16x32_bf16 v[128:131], v[148:151], v[224:227], v[128:131]
	ds_read_b128 v[212:215], v235 offset:8192
	ds_read_b128 v[216:219], v235 offset:10240
	ds_read_b128 v[220:223], v235 offset:12288
	ds_read_b128 v[224:227], v235 offset:14336
	s_waitcnt lgkmcnt(4)
	v_mfma_f32_16x16x32_bf16 v[2:5], v[152:155], v[196:199], v[2:5]
	v_mfma_f32_16x16x32_bf16 v[6:9], v[156:159], v[196:199], v[6:9]
	v_mfma_f32_16x16x32_bf16 v[10:13], v[160:163], v[196:199], v[10:13]
	v_mfma_f32_16x16x32_bf16 v[14:17], v[164:167], v[196:199], v[14:17]
	v_mfma_f32_16x16x32_bf16 v[18:21], v[152:155], v[200:203], v[18:21]
	v_mfma_f32_16x16x32_bf16 v[22:25], v[156:159], v[200:203], v[22:25]
	v_mfma_f32_16x16x32_bf16 v[26:29], v[160:163], v[200:203], v[26:29]
	v_mfma_f32_16x16x32_bf16 v[30:33], v[164:167], v[200:203], v[30:33]
	v_mfma_f32_16x16x32_bf16 v[34:37], v[152:155], v[204:207], v[34:37]
	v_mfma_f32_16x16x32_bf16 v[38:41], v[156:159], v[204:207], v[38:41]
	v_mfma_f32_16x16x32_bf16 v[42:45], v[160:163], v[204:207], v[42:45]
	v_mfma_f32_16x16x32_bf16 v[46:49], v[164:167], v[204:207], v[46:49]
	v_mfma_f32_16x16x32_bf16 v[50:53], v[152:155], v[208:211], v[50:53]
	v_mfma_f32_16x16x32_bf16 v[54:57], v[156:159], v[208:211], v[54:57]
	v_mfma_f32_16x16x32_bf16 v[58:61], v[160:163], v[208:211], v[58:61]
	v_mfma_f32_16x16x32_bf16 v[62:65], v[164:167], v[208:211], v[62:65]
	s_waitcnt lgkmcnt(0)
	v_mfma_f32_16x16x32_bf16 v[66:69], v[152:155], v[212:215], v[66:69]
	v_mfma_f32_16x16x32_bf16 v[70:73], v[156:159], v[212:215], v[70:73]
	v_mfma_f32_16x16x32_bf16 v[74:77], v[160:163], v[212:215], v[74:77]
	v_mfma_f32_16x16x32_bf16 v[78:81], v[164:167], v[212:215], v[78:81]
	v_mfma_f32_16x16x32_bf16 v[82:85], v[152:155], v[216:219], v[82:85]
	v_mfma_f32_16x16x32_bf16 v[86:89], v[156:159], v[216:219], v[86:89]
	v_mfma_f32_16x16x32_bf16 v[92:95], v[160:163], v[216:219], v[92:95]
	v_mfma_f32_16x16x32_bf16 v[96:99], v[164:167], v[216:219], v[96:99]
	v_mfma_f32_16x16x32_bf16 v[100:103], v[152:155], v[220:223], v[100:103]
	v_mfma_f32_16x16x32_bf16 v[104:107], v[156:159], v[220:223], v[104:107]
	v_mfma_f32_16x16x32_bf16 v[108:111], v[160:163], v[220:223], v[108:111]
	v_mfma_f32_16x16x32_bf16 v[112:115], v[164:167], v[220:223], v[112:115]
	v_mfma_f32_16x16x32_bf16 v[116:119], v[152:155], v[224:227], v[116:119]
	v_mfma_f32_16x16x32_bf16 v[120:123], v[156:159], v[224:227], v[120:123]
	v_mfma_f32_16x16x32_bf16 v[124:127], v[160:163], v[224:227], v[124:127]
	v_mfma_f32_16x16x32_bf16 v[128:131], v[164:167], v[224:227], v[128:131]
	s_setprio 0
	s_waitcnt vmcnt(0)
	s_barrier
;     ...
;     if (LEAN) {
; #pragma unroll
;       for (int ks = 0; ks < 2; ++ks) {
;         bf16x8 af[4], bfr[NT];
; #pragma unroll
;         for (int m = 0; m < 4; ++m) af[m] = *(const bf16x8*)(smem + cur + ((abase + m * 2048) ^ (ks * 64)));
; #pragma unroll
;         for (int n = 0; n < NT; ++n) bfr[n] = *(const bf16x8*)(smem + cur + ((bbase + n * 2048) ^ (ks * 64)));
;         __builtin_amdgcn_s_setprio(1);
; #pragma unroll
;         for (int m = 0; m < 4; ++m)
; #pragma unroll
;           for (int n = 0; n < NT; ++n) acc[m][n] = __builtin_amdgcn_mfma_f32_16x16x32_bf16(bfr[n], af[m], acc[m][n], 0, 0, 0);
;         __builtin_amdgcn_s_setprio(0);
;       }
;   __device__ __forceinline__ void next(char* smem) {
;     if (!cnt) { e += nb; return; }
;     if (threadIdx.x == 0) *(volatile int*)smem = (int)tick + nb;
;     __syncthreads();
;     e = *(volatile int*)smem;
;     __syncthreads();
	ds_read_b128 v[136:139], v232
	ds_read_b128 v[140:143], v232 offset:2048
	ds_read_b128 v[144:147], v232 offset:4096
	ds_read_b128 v[148:151], v232 offset:6144
	ds_read_b128 v[196:199], v231 offset:32768
	ds_read_b128 v[200:203], v231 offset:34816
	ds_read_b128 v[204:207], v231 offset:36864
	ds_read_b128 v[208:211], v231 offset:38912
	ds_read_b128 v[152:155], v236
	ds_read_b128 v[156:159], v236 offset:2048
	ds_read_b128 v[160:163], v236 offset:4096
	ds_read_b128 v[164:167], v236 offset:6144
	ds_read_b128 v[212:215], v231 offset:40960
	ds_read_b128 v[216:219], v231 offset:43008
	ds_read_b128 v[220:223], v231 offset:45056
	ds_read_b128 v[224:227], v231 offset:47104
	s_setprio 1
	s_waitcnt lgkmcnt(8)
	v_mfma_f32_16x16x32_bf16 v[2:5], v[136:139], v[196:199], v[2:5]
	v_mfma_f32_16x16x32_bf16 v[6:9], v[140:143], v[196:199], v[6:9]
	v_mfma_f32_16x16x32_bf16 v[10:13], v[144:147], v[196:199], v[10:13]
	v_mfma_f32_16x16x32_bf16 v[14:17], v[148:151], v[196:199], v[14:17]
	v_mfma_f32_16x16x32_bf16 v[18:21], v[136:139], v[200:203], v[18:21]
	v_mfma_f32_16x16x32_bf16 v[22:25], v[140:143], v[200:203], v[22:25]
	v_mfma_f32_16x16x32_bf16 v[26:29], v[144:147], v[200:203], v[26:29]
	v_mfma_f32_16x16x32_bf16 v[30:33], v[148:151], v[200:203], v[30:33]
	v_mfma_f32_16x16x32_bf16 v[34:37], v[136:139], v[204:207], v[34:37]
	v_mfma_f32_16x16x32_bf16 v[38:41], v[140:143], v[204:207], v[38:41]
	v_mfma_f32_16x16x32_bf16 v[42:45], v[144:147], v[204:207], v[42:45]
	v_mfma_f32_16x16x32_bf16 v[46:49], v[148:151], v[204:207], v[46:49]
	v_mfma_f32_16x16x32_bf16 v[50:53], v[136:139], v[208:211], v[50:53]
	v_mfma_f32_16x16x32_bf16 v[54:57], v[140:143], v[208:211], v[54:57]
	v_mfma_f32_16x16x32_bf16 v[58:61], v[144:147], v[208:211], v[58:61]
	v_mfma_f32_16x16x32_bf16 v[62:65], v[148:151], v[208:211], v[62:65]
	s_waitcnt lgkmcnt(0)
	ds_read_b128 v[196:199], v235 offset:32768
	ds_read_b128 v[200:203], v235 offset:34816
	ds_read_b128 v[204:207], v235 offset:36864
	ds_read_b128 v[208:211], v235 offset:38912
	v_mfma_f32_16x16x32_bf16 v[66:69], v[136:139], v[212:215], v[66:69]
	v_mfma_f32_16x16x32_bf16 v[70:73], v[140:143], v[212:215], v[70:73]
	v_mfma_f32_16x16x32_bf16 v[74:77], v[144:147], v[212:215], v[74:77]
	v_mfma_f32_16x16x32_bf16 v[78:81], v[148:151], v[212:215], v[78:81]
	v_mfma_f32_16x16x32_bf16 v[82:85], v[136:139], v[216:219], v[82:85]
	v_mfma_f32_16x16x32_bf16 v[86:89], v[140:143], v[216:219], v[86:89]
	v_mfma_f32_16x16x32_bf16 v[92:95], v[144:147], v[216:219], v[92:95]
	v_mfma_f32_16x16x32_bf16 v[96:99], v[148:151], v[216:219], v[96:99]
	v_mfma_f32_16x16x32_bf16 v[100:103], v[136:139], v[220:223], v[100:103]
	v_mfma_f32_16x16x32_bf16 v[104:107], v[140:143], v[220:223], v[104:107]
	v_mfma_f32_16x16x32_bf16 v[108:111], v[144:147], v[220:223], v[108:111]
	v_mfma_f32_16x16x32_bf16 v[112:115], v[148:151], v[220:223], v[112:115]
	v_mfma_f32_16x16x32_bf16 v[116:119], v[136:139], v[224:227], v[116:119]
	v_mfma_f32_16x16x32_bf16 v[120:123], v[140:143], v[224:227], v[120:123]
	v_mfma_f32_16x16x32_bf16 v[124:127], v[144:147], v[224:227], v[124:127]
	v_mfma_f32_16x16x32_bf16 v[128:131], v[148:151], v[224:227], v[128:131]
	ds_read_b128 v[212:215], v235 offset:40960
	ds_read_b128 v[216:219], v235 offset:43008
	ds_read_b128 v[220:223], v235 offset:45056
	ds_read_b128 v[224:227], v235 offset:47104
	s_waitcnt lgkmcnt(4)
	v_mfma_f32_16x16x32_bf16 v[2:5], v[152:155], v[196:199], v[2:5]
	v_mfma_f32_16x16x32_bf16 v[6:9], v[156:159], v[196:199], v[6:9]
	v_mfma_f32_16x16x32_bf16 v[10:13], v[160:163], v[196:199], v[10:13]
	v_mfma_f32_16x16x32_bf16 v[14:17], v[164:167], v[196:199], v[14:17]
	v_mfma_f32_16x16x32_bf16 v[18:21], v[152:155], v[200:203], v[18:21]
	v_mfma_f32_16x16x32_bf16 v[22:25], v[156:159], v[200:203], v[22:25]
	v_mfma_f32_16x16x32_bf16 v[26:29], v[160:163], v[200:203], v[26:29]
	v_mfma_f32_16x16x32_bf16 v[30:33], v[164:167], v[200:203], v[30:33]
	v_mfma_f32_16x16x32_bf16 v[34:37], v[152:155], v[204:207], v[34:37]
	v_mfma_f32_16x16x32_bf16 v[38:41], v[156:159], v[204:207], v[38:41]
	v_mfma_f32_16x16x32_bf16 v[42:45], v[160:163], v[204:207], v[42:45]
	v_mfma_f32_16x16x32_bf16 v[46:49], v[164:167], v[204:207], v[46:49]
	v_mfma_f32_16x16x32_bf16 v[50:53], v[152:155], v[208:211], v[50:53]
	v_mfma_f32_16x16x32_bf16 v[54:57], v[156:159], v[208:211], v[54:57]
	v_mfma_f32_16x16x32_bf16 v[58:61], v[160:163], v[208:211], v[58:61]
	v_mfma_f32_16x16x32_bf16 v[62:65], v[164:167], v[208:211], v[62:65]
	s_waitcnt lgkmcnt(0)
	v_mfma_f32_16x16x32_bf16 v[66:69], v[152:155], v[212:215], v[66:69]
	v_mfma_f32_16x16x32_bf16 v[70:73], v[156:159], v[212:215], v[70:73]
	v_mfma_f32_16x16x32_bf16 v[74:77], v[160:163], v[212:215], v[74:77]
	v_mfma_f32_16x16x32_bf16 v[78:81], v[164:167], v[212:215], v[78:81]
	v_mfma_f32_16x16x32_bf16 v[82:85], v[152:155], v[216:219], v[82:85]
	v_mfma_f32_16x16x32_bf16 v[86:89], v[156:159], v[216:219], v[86:89]
	v_mfma_f32_16x16x32_bf16 v[92:95], v[160:163], v[216:219], v[92:95]
	v_mfma_f32_16x16x32_bf16 v[96:99], v[164:167], v[216:219], v[96:99]
	v_mfma_f32_16x16x32_bf16 v[100:103], v[152:155], v[220:223], v[100:103]
	v_mfma_f32_16x16x32_bf16 v[104:107], v[156:159], v[220:223], v[104:107]
	v_mfma_f32_16x16x32_bf16 v[108:111], v[160:163], v[220:223], v[108:111]
	v_mfma_f32_16x16x32_bf16 v[112:115], v[164:167], v[220:223], v[112:115]
	v_mfma_f32_16x16x32_bf16 v[116:119], v[152:155], v[224:227], v[116:119]
	v_mfma_f32_16x16x32_bf16 v[120:123], v[156:159], v[224:227], v[120:123]
	v_mfma_f32_16x16x32_bf16 v[124:127], v[160:163], v[224:227], v[124:127]
	v_mfma_f32_16x16x32_bf16 v[128:131], v[164:167], v[224:227], v[128:131]
	s_setprio 0
	s_waitcnt vmcnt(0)
	s_barrier
	s_and_saveexec_b64 s[48:49], s[62:63]
	s_cbranch_execz .Lfu_tk1
	v_add_u32_e32 v0, s73, v233
	ds_write_b32 v1, v0
; __device__ __forceinline__ float silu(float x) { return x * sigm(x); }
;   __device__ __forceinline__ void next(char* smem) {
;     ...
;     if (threadIdx.x == 0) *(volatile int*)smem = (int)tick + nb;
;     __syncthreads();
;     e = *(volatile int*)smem;
;     __syncthreads();
; __device__ __forceinline__ void phase_ffn_up(const Params& p, int half, int mrows, char* smem, unsigned* tk) {
;     ...
;     bf16_t* ob = ACT + (size_t)(tm * 128 + wr * 64 + fr) * DFF + tn * 64 + wc * 32 + fq * 4;
; #pragma unroll
;     for (int m = 0; m < 4; ++m) {
; #pragma unroll
;       for (int np = 0; np < 2; ++np) {
;         float o[4];
; #pragma unroll
;         for (int j = 0; j < 4; ++j) o[j] = silu(acc[m][2 * np][j]) * acc[m][2 * np + 1][j];
;         u32x2 pk; pk.x = pack2(o[0], o[1]); pk.y = pack2(o[2], o[3]);
;         *(u32x2*)(ob + (m * 16) * DFF + np * 16) = pk;
;       }
.Lfu_tk1:
	s_or_b64 exec, exec, s[48:49]
	s_waitcnt lgkmcnt(0)
	s_barrier
	ds_read_b32 v0, v1
	s_waitcnt lgkmcnt(0)
	v_readfirstlane_b32 s44, v0
	s_barrier
	s_mul_i32 s45, s47, 0x160000
	s_add_u32 s48, s100, s45
	s_addc_u32 s49, s101, 0
	s_add_u32 s48, s48, 0x8b80000
	s_addc_u32 s49, s49, 0
	s_lshl_b32 s45, s98, 7
	s_add_u32 s48, s48, s45
	s_addc_u32 s49, s49, 0
	v_mul_f32_e32 v238, 0xbfb8aa3b, v2
	v_mul_f32_e32 v239, 0xbfb8aa3b, v3
	v_mul_f32_e32 v240, 0xbfb8aa3b, v4
	v_mul_f32_e32 v241, 0xbfb8aa3b, v5
	v_exp_f32_e32 v238, v238
	v_exp_f32_e32 v239, v239
	v_exp_f32_e32 v240, v240
	v_exp_f32_e32 v241, v241
	v_add_f32_e32 v238, 1.0, v238
	v_add_f32_e32 v239, 1.0, v239
	v_add_f32_e32 v240, 1.0, v240
	v_add_f32_e32 v241, 1.0, v241
	v_rcp_f32_e32 v238, v238
	v_rcp_f32_e32 v239, v239
	v_rcp_f32_e32 v240, v240
	v_rcp_f32_e32 v241, v241
	v_mul_f32_e32 v2, v2, v238
	v_mul_f32_e32 v3, v3, v239
	v_mul_f32_e32 v4, v4, v240
	v_mul_f32_e32 v5, v5, v241
	v_mul_f32_e32 v2, v6, v2
	v_mul_f32_e32 v3, v7, v3
	v_mul_f32_e32 v4, v8, v4
	v_mul_f32_e32 v5, v9, v5
	v_cvt_pk_bf16_f32 v2, v2, v3
	v_cvt_pk_bf16_f32 v3, v4, v5
	global_store_dwordx2 v234, v[2:3], s[48:49]
	v_mul_f32_e32 v238, 0xbfb8aa3b, v10
	v_mul_f32_e32 v239, 0xbfb8aa3b, v11
	v_mul_f32_e32 v240, 0xbfb8aa3b, v12
	v_mul_f32_e32 v241, 0xbfb8aa3b, v13
	v_exp_f32_e32 v238, v238
	v_exp_f32_e32 v239, v239
	v_exp_f32_e32 v240, v240
	v_exp_f32_e32 v241, v241
	v_add_f32_e32 v238, 1.0, v238
	v_add_f32_e32 v239, 1.0, v239
	v_add_f32_e32 v240, 1.0, v240
	v_add_f32_e32 v241, 1.0, v241
	v_rcp_f32_e32 v238, v238
	v_rcp_f32_e32 v239, v239
	v_rcp_f32_e32 v240, v240
	v_rcp_f32_e32 v241, v241
	v_mul_f32_e32 v10, v10, v238
	v_mul_f32_e32 v11, v11, v239
	v_mul_f32_e32 v12, v12, v240
	v_mul_f32_e32 v13, v13, v241
	v_mul_f32_e32 v10, v14, v10
	v_mul_f32_e32 v11, v15, v11
	v_mul_f32_e32 v12, v16, v12
	v_mul_f32_e32 v13, v17, v13
	v_cvt_pk_bf16_f32 v10, v10, v11
	v_cvt_pk_bf16_f32 v11, v12, v13
	global_store_dwordx2 v234, v[10:11], s[48:49] offset:32
	s_add_u32 s48, s48, 0x16000
	s_addc_u32 s49, s49, 0
	v_mul_f32_e32 v238, 0xbfb8aa3b, v18
	v_mul_f32_e32 v239, 0xbfb8aa3b, v19
	v_mul_f32_e32 v240, 0xbfb8aa3b, v20
	v_mul_f32_e32 v241, 0xbfb8aa3b, v21
	v_exp_f32_e32 v238, v238
	v_exp_f32_e32 v239, v239
	v_exp_f32_e32 v240, v240
	v_exp_f32_e32 v241, v241
	v_add_f32_e32 v238, 1.0, v238
	v_add_f32_e32 v239, 1.0, v239
	v_add_f32_e32 v240, 1.0, v240
	v_add_f32_e32 v241, 1.0, v241
	v_rcp_f32_e32 v238, v238
	v_rcp_f32_e32 v239, v239
	v_rcp_f32_e32 v240, v240
	v_rcp_f32_e32 v241, v241
	v_mul_f32_e32 v18, v18, v238
	v_mul_f32_e32 v19, v19, v239
	v_mul_f32_e32 v20, v20, v240
	v_mul_f32_e32 v21, v21, v241
	v_mul_f32_e32 v18, v22, v18
	v_mul_f32_e32 v19, v23, v19
	v_mul_f32_e32 v20, v24, v20
	v_mul_f32_e32 v21, v25, v21
	v_cvt_pk_bf16_f32 v18, v18, v19
	v_cvt_pk_bf16_f32 v19, v20, v21
	global_store_dwordx2 v234, v[18:19], s[48:49]
	v_mul_f32_e32 v238, 0xbfb8aa3b, v26
	v_mul_f32_e32 v239, 0xbfb8aa3b, v27
	v_mul_f32_e32 v240, 0xbfb8aa3b, v28
	v_mul_f32_e32 v241, 0xbfb8aa3b, v29
	v_exp_f32_e32 v238, v238
	v_exp_f32_e32 v239, v239
	v_exp_f32_e32 v240, v240
	v_exp_f32_e32 v241, v241
	v_add_f32_e32 v238, 1.0, v238
	v_add_f32_e32 v239, 1.0, v239
	v_add_f32_e32 v240, 1.0, v240
	v_add_f32_e32 v241, 1.0, v241
	v_rcp_f32_e32 v238, v238
	v_rcp_f32_e32 v239, v239
	v_rcp_f32_e32 v240, v240
	v_rcp_f32_e32 v241, v241
	v_mul_f32_e32 v26, v26, v238
	v_mul_f32_e32 v27, v27, v239
	v_mul_f32_e32 v28, v28, v240
	v_mul_f32_e32 v29, v29, v241
	v_mul_f32_e32 v26, v30, v26
	v_mul_f32_e32 v27, v31, v27
	v_mul_f32_e32 v28, v32, v28
	v_mul_f32_e32 v29, v33, v29
	v_cvt_pk_bf16_f32 v26, v26, v27
	v_cvt_pk_bf16_f32 v27, v28, v29
	global_store_dwordx2 v234, v[26:27], s[48:49] offset:32
	s_add_u32 s48, s48, 0x16000
	s_addc_u32 s49, s49, 0
	v_mul_f32_e32 v238, 0xbfb8aa3b, v34
	v_mul_f32_e32 v239, 0xbfb8aa3b, v35
	v_mul_f32_e32 v240, 0xbfb8aa3b, v36
	v_mul_f32_e32 v241, 0xbfb8aa3b, v37
	v_exp_f32_e32 v238, v238
	v_exp_f32_e32 v239, v239
	v_exp_f32_e32 v240, v240
	v_exp_f32_e32 v241, v241
	v_add_f32_e32 v238, 1.0, v238
	v_add_f32_e32 v239, 1.0, v239
	v_add_f32_e32 v240, 1.0, v240
	v_add_f32_e32 v241, 1.0, v241
	v_rcp_f32_e32 v238, v238
	v_rcp_f32_e32 v239, v239
	v_rcp_f32_e32 v240, v240
	v_rcp_f32_e32 v241, v241
	v_mul_f32_e32 v34, v34, v238
	v_mul_f32_e32 v35, v35, v239
	v_mul_f32_e32 v36, v36, v240
	v_mul_f32_e32 v37, v37, v241
	v_mul_f32_e32 v34, v38, v34
	v_mul_f32_e32 v35, v39, v35
	v_mul_f32_e32 v36, v40, v36
	v_mul_f32_e32 v37, v41, v37
	v_cvt_pk_bf16_f32 v34, v34, v35
	v_cvt_pk_bf16_f32 v35, v36, v37
	global_store_dwordx2 v234, v[34:35], s[48:49]
	v_mul_f32_e32 v238, 0xbfb8aa3b, v42
	v_mul_f32_e32 v239, 0xbfb8aa3b, v43
	v_mul_f32_e32 v240, 0xbfb8aa3b, v44
	v_mul_f32_e32 v241, 0xbfb8aa3b, v45
	v_exp_f32_e32 v238, v238
	v_exp_f32_e32 v239, v239
	v_exp_f32_e32 v240, v240
	v_exp_f32_e32 v241, v241
	v_add_f32_e32 v238, 1.0, v238
	v_add_f32_e32 v239, 1.0, v239
	v_add_f32_e32 v240, 1.0, v240
	v_add_f32_e32 v241, 1.0, v241
	v_rcp_f32_e32 v238, v238
	v_rcp_f32_e32 v239, v239
	v_rcp_f32_e32 v240, v240
	v_rcp_f32_e32 v241, v241
	v_mul_f32_e32 v42, v42, v238
	v_mul_f32_e32 v43, v43, v239
	v_mul_f32_e32 v44, v44, v240
	v_mul_f32_e32 v45, v45, v241
	v_mul_f32_e32 v42, v46, v42
	v_mul_f32_e32 v43, v47, v43
	v_mul_f32_e32 v44, v48, v44
	v_mul_f32_e32 v45, v49, v45
	v_cvt_pk_bf16_f32 v42, v42, v43
	v_cvt_pk_bf16_f32 v43, v44, v45
	global_store_dwordx2 v234, v[42:43], s[48:49] offset:32
	s_add_u32 s48, s48, 0x16000
	s_addc_u32 s49, s49, 0
	v_mul_f32_e32 v238, 0xbfb8aa3b, v50
	v_mul_f32_e32 v239, 0xbfb8aa3b, v51
	v_mul_f32_e32 v240, 0xbfb8aa3b, v52
	v_mul_f32_e32 v241, 0xbfb8aa3b, v53
; __device__ __forceinline__ float silu(float x) { return x * sigm(x); }
; __device__ __forceinline__ void phase_ffn_up(const Params& p, int half, int mrows, char* smem, unsigned* tk) {
;     ...
;     bf16_t* ob = ACT + (size_t)(tm * 128 + wr * 64 + fr) * DFF + tn * 64 + wc * 32 + fq * 4;
; #pragma unroll
;     for (int m = 0; m < 4; ++m) {
; #pragma unroll
;       for (int np = 0; np < 2; ++np) {
;         float o[4];
; #pragma unroll
;         for (int j = 0; j < 4; ++j) o[j] = silu(acc[m][2 * np][j]) * acc[m][2 * np + 1][j];
;         u32x2 pk; pk.x = pack2(o[0], o[1]); pk.y = pack2(o[2], o[3]);
;         *(u32x2*)(ob + (m * 16) * DFF + np * 16) = pk;
;       }
;       __builtin_amdgcn_sched_barrier(0);
;     }
	v_exp_f32_e32 v238, v238
	v_exp_f32_e32 v239, v239
	v_exp_f32_e32 v240, v240
	v_exp_f32_e32 v241, v241
	v_add_f32_e32 v238, 1.0, v238
	v_add_f32_e32 v239, 1.0, v239
	v_add_f32_e32 v240, 1.0, v240
	v_add_f32_e32 v241, 1.0, v241
	v_rcp_f32_e32 v238, v238
	v_rcp_f32_e32 v239, v239
	v_rcp_f32_e32 v240, v240
	v_rcp_f32_e32 v241, v241
	v_mul_f32_e32 v50, v50, v238
	v_mul_f32_e32 v51, v51, v239
	v_mul_f32_e32 v52, v52, v240
	v_mul_f32_e32 v53, v53, v241
	v_mul_f32_e32 v50, v54, v50
	v_mul_f32_e32 v51, v55, v51
	v_mul_f32_e32 v52, v56, v52
	v_mul_f32_e32 v53, v57, v53
	v_cvt_pk_bf16_f32 v50, v50, v51
	v_cvt_pk_bf16_f32 v51, v52, v53
	global_store_dwordx2 v234, v[50:51], s[48:49]
	v_mul_f32_e32 v238, 0xbfb8aa3b, v58
	v_mul_f32_e32 v239, 0xbfb8aa3b, v59
	v_mul_f32_e32 v240, 0xbfb8aa3b, v60
	v_mul_f32_e32 v241, 0xbfb8aa3b, v61
	v_exp_f32_e32 v238, v238
	v_exp_f32_e32 v239, v239
	v_exp_f32_e32 v240, v240
	v_exp_f32_e32 v241, v241
	v_add_f32_e32 v238, 1.0, v238
	v_add_f32_e32 v239, 1.0, v239
	v_add_f32_e32 v240, 1.0, v240
	v_add_f32_e32 v241, 1.0, v241
	v_rcp_f32_e32 v238, v238
	v_rcp_f32_e32 v239, v239
	v_rcp_f32_e32 v240, v240
	v_rcp_f32_e32 v241, v241
	v_mul_f32_e32 v58, v58, v238
	v_mul_f32_e32 v59, v59, v239
	v_mul_f32_e32 v60, v60, v240
	v_mul_f32_e32 v61, v61, v241
	v_mul_f32_e32 v58, v62, v58
	v_mul_f32_e32 v59, v63, v59
	v_mul_f32_e32 v60, v64, v60
	v_mul_f32_e32 v61, v65, v61
	v_cvt_pk_bf16_f32 v58, v58, v59
	v_cvt_pk_bf16_f32 v59, v60, v61
	global_store_dwordx2 v234, v[58:59], s[48:49] offset:32
	s_add_u32 s48, s48, 0x16000
	s_addc_u32 s49, s49, 0
	v_mul_f32_e32 v238, 0xbfb8aa3b, v66
	v_mul_f32_e32 v239, 0xbfb8aa3b, v67
	v_mul_f32_e32 v240, 0xbfb8aa3b, v68
	v_mul_f32_e32 v241, 0xbfb8aa3b, v69
	v_exp_f32_e32 v238, v238
	v_exp_f32_e32 v239, v239
	v_exp_f32_e32 v240, v240
	v_exp_f32_e32 v241, v241
	v_add_f32_e32 v238, 1.0, v238
	v_add_f32_e32 v239, 1.0, v239
	v_add_f32_e32 v240, 1.0, v240
	v_add_f32_e32 v241, 1.0, v241
	v_rcp_f32_e32 v238, v238
	v_rcp_f32_e32 v239, v239
	v_rcp_f32_e32 v240, v240
	v_rcp_f32_e32 v241, v241
	v_mul_f32_e32 v66, v66, v238
	v_mul_f32_e32 v67, v67, v239
	v_mul_f32_e32 v68, v68, v240
	v_mul_f32_e32 v69, v69, v241
	v_mul_f32_e32 v66, v70, v66
	v_mul_f32_e32 v67, v71, v67
	v_mul_f32_e32 v68, v72, v68
	v_mul_f32_e32 v69, v73, v69
	v_cvt_pk_bf16_f32 v66, v66, v67
	v_cvt_pk_bf16_f32 v67, v68, v69
	global_store_dwordx2 v234, v[66:67], s[48:49]
	v_mul_f32_e32 v238, 0xbfb8aa3b, v74
	v_mul_f32_e32 v239, 0xbfb8aa3b, v75
	v_mul_f32_e32 v240, 0xbfb8aa3b, v76
	v_mul_f32_e32 v241, 0xbfb8aa3b, v77
	v_exp_f32_e32 v238, v238
	v_exp_f32_e32 v239, v239
	v_exp_f32_e32 v240, v240
	v_exp_f32_e32 v241, v241
	v_add_f32_e32 v238, 1.0, v238
	v_add_f32_e32 v239, 1.0, v239
	v_add_f32_e32 v240, 1.0, v240
	v_add_f32_e32 v241, 1.0, v241
	v_rcp_f32_e32 v238, v238
	v_rcp_f32_e32 v239, v239
	v_rcp_f32_e32 v240, v240
	v_rcp_f32_e32 v241, v241
	v_mul_f32_e32 v74, v74, v238
	v_mul_f32_e32 v75, v75, v239
	v_mul_f32_e32 v76, v76, v240
	v_mul_f32_e32 v77, v77, v241
	v_mul_f32_e32 v74, v78, v74
	v_mul_f32_e32 v75, v79, v75
	v_mul_f32_e32 v76, v80, v76
	v_mul_f32_e32 v77, v81, v77
	v_cvt_pk_bf16_f32 v74, v74, v75
	v_cvt_pk_bf16_f32 v75, v76, v77
	global_store_dwordx2 v234, v[74:75], s[48:49] offset:32
	s_add_u32 s48, s48, 0x16000
	s_addc_u32 s49, s49, 0
	v_mul_f32_e32 v238, 0xbfb8aa3b, v82
	v_mul_f32_e32 v239, 0xbfb8aa3b, v83
	v_mul_f32_e32 v240, 0xbfb8aa3b, v84
	v_mul_f32_e32 v241, 0xbfb8aa3b, v85
	v_exp_f32_e32 v238, v238
	v_exp_f32_e32 v239, v239
	v_exp_f32_e32 v240, v240
	v_exp_f32_e32 v241, v241
	v_add_f32_e32 v238, 1.0, v238
	v_add_f32_e32 v239, 1.0, v239
	v_add_f32_e32 v240, 1.0, v240
	v_add_f32_e32 v241, 1.0, v241
	v_rcp_f32_e32 v238, v238
	v_rcp_f32_e32 v239, v239
	v_rcp_f32_e32 v240, v240
	v_rcp_f32_e32 v241, v241
	v_mul_f32_e32 v82, v82, v238
	v_mul_f32_e32 v83, v83, v239
	v_mul_f32_e32 v84, v84, v240
	v_mul_f32_e32 v85, v85, v241
	v_mul_f32_e32 v82, v86, v82
	v_mul_f32_e32 v83, v87, v83
	v_mul_f32_e32 v84, v88, v84
	v_mul_f32_e32 v85, v89, v85
	v_cvt_pk_bf16_f32 v82, v82, v83
	v_cvt_pk_bf16_f32 v83, v84, v85
	global_store_dwordx2 v234, v[82:83], s[48:49]
	v_mul_f32_e32 v238, 0xbfb8aa3b, v92
	v_mul_f32_e32 v239, 0xbfb8aa3b, v93
	v_mul_f32_e32 v240, 0xbfb8aa3b, v94
	v_mul_f32_e32 v241, 0xbfb8aa3b, v95
	v_exp_f32_e32 v238, v238
	v_exp_f32_e32 v239, v239
	v_exp_f32_e32 v240, v240
	v_exp_f32_e32 v241, v241
	v_add_f32_e32 v238, 1.0, v238
	v_add_f32_e32 v239, 1.0, v239
	v_add_f32_e32 v240, 1.0, v240
	v_add_f32_e32 v241, 1.0, v241
	v_rcp_f32_e32 v238, v238
	v_rcp_f32_e32 v239, v239
	v_rcp_f32_e32 v240, v240
	v_rcp_f32_e32 v241, v241
	v_mul_f32_e32 v92, v92, v238
	v_mul_f32_e32 v93, v93, v239
	v_mul_f32_e32 v94, v94, v240
	v_mul_f32_e32 v95, v95, v241
	v_mul_f32_e32 v92, v96, v92
	v_mul_f32_e32 v93, v97, v93
	v_mul_f32_e32 v94, v98, v94
	v_mul_f32_e32 v95, v99, v95
	v_cvt_pk_bf16_f32 v92, v92, v93
	v_cvt_pk_bf16_f32 v93, v94, v95
	global_store_dwordx2 v234, v[92:93], s[48:49] offset:32
	s_add_u32 s48, s48, 0x16000
	s_addc_u32 s49, s49, 0
	v_mul_f32_e32 v238, 0xbfb8aa3b, v100
	v_mul_f32_e32 v239, 0xbfb8aa3b, v101
	v_mul_f32_e32 v240, 0xbfb8aa3b, v102
	v_mul_f32_e32 v241, 0xbfb8aa3b, v103
	v_exp_f32_e32 v238, v238
	v_exp_f32_e32 v239, v239
	v_exp_f32_e32 v240, v240
	v_exp_f32_e32 v241, v241
	v_add_f32_e32 v238, 1.0, v238
	v_add_f32_e32 v239, 1.0, v239
	v_add_f32_e32 v240, 1.0, v240
	v_add_f32_e32 v241, 1.0, v241
	v_rcp_f32_e32 v238, v238
	v_rcp_f32_e32 v239, v239
	v_rcp_f32_e32 v240, v240
; __device__ __forceinline__ float silu(float x) { return x * sigm(x); }
; __device__ __forceinline__ void phase_ffn_up(const Params& p, int half, int mrows, char* smem, unsigned* tk) {
;     ...
;     bf16_t* ob = ACT + (size_t)(tm * 128 + wr * 64 + fr) * DFF + tn * 64 + wc * 32 + fq * 4;
; #pragma unroll
;     for (int m = 0; m < 4; ++m) {
; #pragma unroll
;       for (int np = 0; np < 2; ++np) {
;         float o[4];
; #pragma unroll
;         for (int j = 0; j < 4; ++j) o[j] = silu(acc[m][2 * np][j]) * acc[m][2 * np + 1][j];
;         u32x2 pk; pk.x = pack2(o[0], o[1]); pk.y = pack2(o[2], o[3]);
;         *(u32x2*)(ob + (m * 16) * DFF + np * 16) = pk;
;       }
;       __builtin_amdgcn_sched_barrier(0);
;     }
	v_rcp_f32_e32 v241, v241
	v_mul_f32_e32 v100, v100, v238
	v_mul_f32_e32 v101, v101, v239
	v_mul_f32_e32 v102, v102, v240
	v_mul_f32_e32 v103, v103, v241
	v_mul_f32_e32 v100, v104, v100
	v_mul_f32_e32 v101, v105, v101
	v_mul_f32_e32 v102, v106, v102
	v_mul_f32_e32 v103, v107, v103
	v_cvt_pk_bf16_f32 v100, v100, v101
	v_cvt_pk_bf16_f32 v101, v102, v103
	global_store_dwordx2 v234, v[100:101], s[48:49]
	v_mul_f32_e32 v238, 0xbfb8aa3b, v108
	v_mul_f32_e32 v239, 0xbfb8aa3b, v109
	v_mul_f32_e32 v240, 0xbfb8aa3b, v110
	v_mul_f32_e32 v241, 0xbfb8aa3b, v111
	v_exp_f32_e32 v238, v238
	v_exp_f32_e32 v239, v239
	v_exp_f32_e32 v240, v240
	v_exp_f32_e32 v241, v241
	v_add_f32_e32 v238, 1.0, v238
	v_add_f32_e32 v239, 1.0, v239
	v_add_f32_e32 v240, 1.0, v240
	v_add_f32_e32 v241, 1.0, v241
	v_rcp_f32_e32 v238, v238
	v_rcp_f32_e32 v239, v239
	v_rcp_f32_e32 v240, v240
	v_rcp_f32_e32 v241, v241
	v_mul_f32_e32 v108, v108, v238
	v_mul_f32_e32 v109, v109, v239
	v_mul_f32_e32 v110, v110, v240
	v_mul_f32_e32 v111, v111, v241
	v_mul_f32_e32 v108, v112, v108
	v_mul_f32_e32 v109, v113, v109
	v_mul_f32_e32 v110, v114, v110
	v_mul_f32_e32 v111, v115, v111
	v_cvt_pk_bf16_f32 v108, v108, v109
	v_cvt_pk_bf16_f32 v109, v110, v111
	global_store_dwordx2 v234, v[108:109], s[48:49] offset:32
	s_add_u32 s48, s48, 0x16000
	s_addc_u32 s49, s49, 0
	v_mul_f32_e32 v238, 0xbfb8aa3b, v116
	v_mul_f32_e32 v239, 0xbfb8aa3b, v117
	v_mul_f32_e32 v240, 0xbfb8aa3b, v118
	v_mul_f32_e32 v241, 0xbfb8aa3b, v119
	v_exp_f32_e32 v238, v238
	v_exp_f32_e32 v239, v239
	v_exp_f32_e32 v240, v240
	v_exp_f32_e32 v241, v241
	v_add_f32_e32 v238, 1.0, v238
	v_add_f32_e32 v239, 1.0, v239
	v_add_f32_e32 v240, 1.0, v240
	v_add_f32_e32 v241, 1.0, v241
	v_rcp_f32_e32 v238, v238
	v_rcp_f32_e32 v239, v239
	v_rcp_f32_e32 v240, v240
	v_rcp_f32_e32 v241, v241
	v_mul_f32_e32 v116, v116, v238
	v_mul_f32_e32 v117, v117, v239
	v_mul_f32_e32 v118, v118, v240
	v_mul_f32_e32 v119, v119, v241
	v_mul_f32_e32 v116, v120, v116
	v_mul_f32_e32 v117, v121, v117
	v_mul_f32_e32 v118, v122, v118
	v_mul_f32_e32 v119, v123, v119
	v_cvt_pk_bf16_f32 v116, v116, v117
	v_cvt_pk_bf16_f32 v117, v118, v119
	global_store_dwordx2 v234, v[116:117], s[48:49]
	v_mul_f32_e32 v238, 0xbfb8aa3b, v124
	v_mul_f32_e32 v239, 0xbfb8aa3b, v125
	v_mul_f32_e32 v240, 0xbfb8aa3b, v126
	v_mul_f32_e32 v241, 0xbfb8aa3b, v127
	v_exp_f32_e32 v238, v238
	v_exp_f32_e32 v239, v239
	v_exp_f32_e32 v240, v240
	v_exp_f32_e32 v241, v241
	v_add_f32_e32 v238, 1.0, v238
	v_add_f32_e32 v239, 1.0, v239
	v_add_f32_e32 v240, 1.0, v240
	v_add_f32_e32 v241, 1.0, v241
	v_rcp_f32_e32 v238, v238
	v_rcp_f32_e32 v239, v239
	v_rcp_f32_e32 v240, v240
	v_rcp_f32_e32 v241, v241
	v_mul_f32_e32 v124, v124, v238
	v_mul_f32_e32 v125, v125, v239
	v_mul_f32_e32 v126, v126, v240
	v_mul_f32_e32 v127, v127, v241
	v_mul_f32_e32 v124, v128, v124
	v_mul_f32_e32 v125, v129, v125
	v_mul_f32_e32 v126, v130, v126
	v_mul_f32_e32 v127, v131, v127
	v_cvt_pk_bf16_f32 v124, v124, v125
	v_cvt_pk_bf16_f32 v125, v126, v127
	global_store_dwordx2 v234, v[124:125], s[48:49] offset:32
	s_branch .Lfu_tile
.Lfu_exit:
	s_waitcnt vmcnt(0) lgkmcnt(0)
	v_readlane_b32 s40, v249, 0
	v_readlane_b32 s41, v249, 1
	v_readlane_b32 s42, v249, 2
	v_readlane_b32 s43, v249, 3
	v_readlane_b32 s44, v249, 4
	v_readlane_b32 s45, v249, 5
	v_readlane_b32 s46, v249, 6
	v_readlane_b32 s47, v249, 7
	v_mov_b32_e32 v92, s40
	v_mov_b32_e32 v93, s41
	v_mov_b32_e32 v94, s42
	v_mov_b32_e32 v95, s43
	v_mov_b32_e32 v96, s44
	v_mov_b32_e32 v97, s45
	v_mov_b32_e32 v98, s46
	v_mov_b32_e32 v99, s47
	v_readlane_b32 s40, v249, 8
	v_readlane_b32 s41, v249, 9
	v_readlane_b32 s42, v249, 10
	v_readlane_b32 s43, v249, 11
	v_readlane_b32 s44, v249, 12
	v_readlane_b32 s45, v249, 13
	v_readlane_b32 s46, v249, 14
	v_readlane_b32 s47, v249, 15
	v_mov_b32_e32 v100, s40
	v_mov_b32_e32 v101, s41
	v_mov_b32_e32 v102, s42
	v_mov_b32_e32 v103, s43
	v_mov_b32_e32 v104, s44
	v_mov_b32_e32 v105, s45
	v_mov_b32_e32 v106, s46
	v_mov_b32_e32 v107, s47
	v_readlane_b32 s40, v249, 16
	v_readlane_b32 s41, v249, 17
	v_readlane_b32 s42, v249, 18
	v_readlane_b32 s43, v249, 19
	v_readlane_b32 s44, v249, 20
	v_readlane_b32 s45, v249, 21
	v_readlane_b32 s46, v249, 22
	v_readlane_b32 s47, v249, 23
	v_mov_b32_e32 v108, s40
	v_mov_b32_e32 v109, s41
	v_mov_b32_e32 v110, s42
	v_mov_b32_e32 v111, s43
	v_mov_b32_e32 v112, s44
	v_mov_b32_e32 v113, s45
	v_mov_b32_e32 v114, s46
	v_mov_b32_e32 v115, s47
	v_readlane_b32 s40, v249, 24
	v_readlane_b32 s41, v249, 25
	v_readlane_b32 s42, v249, 26
	v_readlane_b32 s43, v249, 27
	v_readlane_b32 s44, v249, 28
	v_readlane_b32 s45, v249, 29
	v_readlane_b32 s46, v249, 30
	v_readlane_b32 s47, v249, 31
	v_mov_b32_e32 v116, s40
	v_mov_b32_e32 v117, s41
	v_mov_b32_e32 v118, s42
	v_mov_b32_e32 v119, s43
	v_mov_b32_e32 v120, s44
	v_mov_b32_e32 v121, s45
	v_mov_b32_e32 v122, s46
	v_mov_b32_e32 v123, s47
	v_readlane_b32 s40, v249, 32
	v_readlane_b32 s41, v249, 33
	v_readlane_b32 s42, v249, 34
	v_readlane_b32 s43, v249, 35
	v_readlane_b32 s44, v249, 36
	v_readlane_b32 s45, v249, 37
	v_readlane_b32 s46, v249, 38
	v_readlane_b32 s47, v249, 39
	v_mov_b32_e32 v124, s40
	v_mov_b32_e32 v125, s41
	v_mov_b32_e32 v126, s42
	v_mov_b32_e32 v127, s43
	v_mov_b32_e32 v128, s44
	v_mov_b32_e32 v129, s45
	v_mov_b32_e32 v130, s46
	v_mov_b32_e32 v131, s47
	v_readlane_b32 s40, v249, 40
	v_readlane_b32 s41, v249, 41
	s_nop 1
	v_mov_b32_e32 v132, s40
	v_mov_b32_e32 v133, s41
	s_mov_b64 s[44:45], 0x1000
	s_branch .LBB0_329

; __global__ void __launch_bounds__(256, 2) fwd_megakernel(Params p) {
;   __shared__ __attribute__((aligned(16))) char smem[65536];
	.amdhsa_kernel _Z14fwd_megakernel6Params
		.amdhsa_group_segment_fixed_size 81920
		.amdhsa_private_segment_fixed_size 0
		.amdhsa_kernarg_size 1976
		.amdhsa_user_sgpr_count 2
		.amdhsa_user_sgpr_dispatch_ptr 0
		.amdhsa_user_sgpr_queue_ptr 0
		.amdhsa_user_sgpr_kernarg_segment_ptr 1
		.amdhsa_user_sgpr_dispatch_id 0
		.amdhsa_user_sgpr_kernarg_preload_length 0
		.amdhsa_user_sgpr_kernarg_preload_offset 0
		.amdhsa_user_sgpr_private_segment_size 0
		.amdhsa_uses_dynamic_stack 0
		.amdhsa_enable_private_segment 0
		.amdhsa_system_sgpr_workgroup_id_x 1
		.amdhsa_system_sgpr_workgroup_id_y 0
		.amdhsa_system_sgpr_workgroup_id_z 0
		.amdhsa_system_sgpr_workgroup_info 0
		.amdhsa_system_vgpr_workitem_id 2
		.amdhsa_next_free_vgpr 252
		.amdhsa_next_free_sgpr 102
		.amdhsa_accum_offset 252
		.amdhsa_reserve_vcc 1
		.amdhsa_float_round_mode_32 0
		.amdhsa_float_round_mode_16_64 0
		.amdhsa_float_denorm_mode_32 3
		.amdhsa_float_denorm_mode_16_64 3
		.amdhsa_dx10_clamp 1
		.amdhsa_ieee_mode 1
		.amdhsa_fp16_overflow 0
		.amdhsa_tg_split 0
		.amdhsa_exception_fp_ieee_invalid_op 0
		.amdhsa_exception_fp_denorm_src 0
		.amdhsa_exception_fp_ieee_div_zero 0
		.amdhsa_exception_fp_ieee_overflow 0
		.amdhsa_exception_fp_ieee_underflow 0
		.amdhsa_exception_fp_ieee_inexact 0
		.amdhsa_exception_int_div_zero 0
	.end_amdhsa_kernel

; __global__ void __launch_bounds__(256, 2) fwd_megakernel(Params p) {
;   __shared__ __attribute__((aligned(16))) char smem[65536];
amdhsa.kernels:
  - .agpr_count:     0
    .args:
      - .offset:         0
        .size:           1720
        .value_kind:     by_value
      - .offset:         1720
        .size:           4
        .value_kind:     hidden_block_count_x
      - .offset:         1724
        .size:           4
        .value_kind:     hidden_block_count_y
      - .offset:         1728
        .size:           4
        .value_kind:     hidden_block_count_z
      - .offset:         1732
        .size:           2
        .value_kind:     hidden_group_size_x
      - .offset:         1734
        .size:           2
        .value_kind:     hidden_group_size_y
      - .offset:         1736
        .size:           2
        .value_kind:     hidden_group_size_z
      - .offset:         1738
        .size:           2
        .value_kind:     hidden_remainder_x
      - .offset:         1740
        .size:           2
        .value_kind:     hidden_remainder_y
      - .offset:         1742
        .size:           2
        .value_kind:     hidden_remainder_z
      - .offset:         1760
        .size:           8
        .value_kind:     hidden_global_offset_x
      - .offset:         1768
        .size:           8
        .value_kind:     hidden_global_offset_y
      - .offset:         1776
        .size:           8
        .value_kind:     hidden_global_offset_z
      - .offset:         1784
        .size:           2
        .value_kind:     hidden_grid_dims
      - .offset:         1808
        .size:           8
        .value_kind:     hidden_multigrid_sync_arg
    .group_segment_fixed_size: 81920
    .kernarg_segment_align: 8
    .kernarg_segment_size: 1976
    .language:       OpenCL C
    .language_version:
      - 2
      - 0
    .max_flat_workgroup_size: 256
    .name:           _Z14fwd_megakernel6Params
    .private_segment_fixed_size: 0
    .sgpr_count:     108
    .sgpr_spill_count: 109
    .symbol:         _Z14fwd_megakernel6Params.kd
    .uniform_work_group_size: 1
    .uses_dynamic_stack: false
    .vgpr_count:     252
    .vgpr_spill_count: 0
    .wavefront_size: 64
